# GEMM K-loops: loop-control + next-iteration pointer-select SALU rotated out of the post-barrier load-segment head into the last MFMA burst
# baseline (speedup 1.0000x reference)
; template <class Epi, class Sched, bool ALIGN_EPI = false, bool SP2 = false>
; __device__ __forceinline__ void gemm_phase(PG8_LAS unsigned char* lds, const Gemm g, const Sched& S, const Epi& E) {
;     ...
;         const bool has_next = S.next(ui + 1, nxt);
;         const char* nA = has_next ? (const char*)g.A + (size_t)nxt.pm * tstep : cA; const char* nB = has_next ? (const char*)g.Bt + (size_t)nxt.pn * tstep : cB;
;         for (int t = 0; t < nt; t += 2) {
;             const bool last = (t == nt - 2);
;             const char* a1 = cA + (size_t)(t + 1) * kstep;
;             const char* a2 = last ? nA : cA + (size_t)(t + 2) * kstep; const char* b2 = last ? nB : cB + (size_t)(t + 2) * kstep;
;     ...
; #pragma unroll
;         for (int a = 0; a < 2; ++a)
; #pragma unroll
;             for (int b = 0; b < 2; ++b)
; #pragma unroll
;                 for (int m = 0; m < 4; ++m)
; #pragma unroll
;                     for (int n = 0; n < 2; ++n) acc[a][b][m][n] = (f32x4){0.f, 0.f, 0.f, 0.f};
;         cur = nxt; cA = nA; cB = nB; ++ui;
.LBB0_425:
	s_ashr_i32 s41, s40, 31
	s_lshl_b64 s[26:27], s[40:41], 19
	s_add_u32 s60, s72, s26
	s_addc_u32 s61, s73, s27
	s_and_b64 s[26:27], s[36:37], exec
	s_cselect_b32 s41, s61, s47
	s_cselect_b32 s92, s60, s46
	s_ashr_i32 s39, s38, 31
	s_lshl_b64 s[26:27], s[38:39], 19
	s_add_u32 s74, s30, s26
	s_addc_u32 s75, s52, s27
	s_and_b64 s[26:27], s[36:37], exec
	s_cselect_b32 s39, s75, s43
	s_cselect_b32 s93, s74, s42
	s_add_u32 s26, s46, 0x40080
	s_addc_u32 s27, s47, 0
	s_add_u32 vcc_lo, s42, 0x100
	v_mov_b32_e32 v0, 0
	s_addc_u32 s94, s43, 0
	s_mov_b32 s95, -2
	v_mov_b32_e32 v1, v0
	v_mov_b32_e32 v2, v0
	v_mov_b32_e32 v3, v0
	v_mov_b32_e32 v4, v0
	v_mov_b32_e32 v5, v0
	v_mov_b32_e32 v6, v0
	v_mov_b32_e32 v7, v0
	v_mov_b32_e32 v16, v0
	v_mov_b32_e32 v17, v0
	v_mov_b32_e32 v18, v0
	v_mov_b32_e32 v19, v0
	v_mov_b32_e32 v20, v0
	v_mov_b32_e32 v21, v0
	v_mov_b32_e32 v22, v0
	v_mov_b32_e32 v23, v0
	s_waitcnt vmcnt(0)
	v_mov_b32_e32 v32, v0
	v_mov_b32_e32 v33, v0
	v_mov_b32_e32 v34, v0
	v_mov_b32_e32 v35, v0
	v_mov_b32_e32 v36, v0
	v_mov_b32_e32 v37, v0
	v_mov_b32_e32 v38, v0
	v_mov_b32_e32 v39, v0
	v_mov_b32_e32 v48, v0
	v_mov_b32_e32 v49, v0
	v_mov_b32_e32 v50, v0
	v_mov_b32_e32 v51, v0
	v_mov_b32_e32 v52, v0
	v_mov_b32_e32 v53, v0
	v_mov_b32_e32 v54, v0
	v_mov_b32_e32 v55, v0
	v_mov_b32_e32 v8, v0
	v_mov_b32_e32 v9, v0
	v_mov_b32_e32 v10, v0
	v_mov_b32_e32 v11, v0
	v_mov_b32_e32 v12, v0
	v_mov_b32_e32 v13, v0
	v_mov_b32_e32 v14, v0
	v_mov_b32_e32 v15, v0
	v_mov_b32_e32 v24, v0
	v_mov_b32_e32 v25, v0
	v_mov_b32_e32 v26, v0
	v_mov_b32_e32 v27, v0
	v_mov_b32_e32 v28, v0
	v_mov_b32_e32 v29, v0
	v_mov_b32_e32 v30, v0
	v_mov_b32_e32 v31, v0
	v_mov_b32_e32 v40, v0
	v_mov_b32_e32 v41, v0
	v_mov_b32_e32 v42, v0
	v_mov_b32_e32 v43, v0
	v_mov_b32_e32 v44, v0
	v_mov_b32_e32 v45, v0
	v_mov_b32_e32 v46, v0
	v_mov_b32_e32 v47, v0
	v_mov_b32_e32 v56, v0
	v_mov_b32_e32 v57, v0
	v_mov_b32_e32 v58, v0
	v_mov_b32_e32 v59, v0
	v_mov_b32_e32 v60, v0
	v_mov_b32_e32 v61, v0
	v_mov_b32_e32 v62, v0
	v_mov_b32_e32 v63, v0
	v_mov_b32_e32 v64, v0
	v_mov_b32_e32 v65, v0
	v_mov_b32_e32 v66, v0
	v_mov_b32_e32 v67, v0
	v_mov_b32_e32 v68, v0
	v_mov_b32_e32 v69, v0
	v_mov_b32_e32 v70, v0
	v_mov_b32_e32 v71, v0
	v_mov_b32_e32 v80, v0
	v_mov_b32_e32 v81, v0
	v_mov_b32_e32 v82, v0
	v_mov_b32_e32 v83, v0
	v_mov_b32_e32 v84, v0
	v_mov_b32_e32 v85, v0
	v_mov_b32_e32 v86, v0
	v_mov_b32_e32 v87, v0
	v_mov_b32_e32 v96, v0
	v_mov_b32_e32 v97, v0
	v_mov_b32_e32 v98, v0
	v_mov_b32_e32 v99, v0
	v_mov_b32_e32 v100, v0
	v_mov_b32_e32 v101, v0
	v_mov_b32_e32 v102, v0
	v_mov_b32_e32 v103, v0
	v_mov_b32_e32 v112, v0
	v_mov_b32_e32 v113, v0
	v_mov_b32_e32 v114, v0
	v_mov_b32_e32 v115, v0
	v_mov_b32_e32 v116, v0
	v_mov_b32_e32 v117, v0
	v_mov_b32_e32 v118, v0
	v_mov_b32_e32 v119, v0
	v_mov_b32_e32 v72, v0
	v_mov_b32_e32 v73, v0
	v_mov_b32_e32 v74, v0
	v_mov_b32_e32 v75, v0
	v_mov_b32_e32 v76, v0
	v_mov_b32_e32 v77, v0
	v_mov_b32_e32 v78, v0
	v_mov_b32_e32 v79, v0
	v_mov_b32_e32 v88, v0
	v_mov_b32_e32 v89, v0
	v_mov_b32_e32 v90, v0
	v_mov_b32_e32 v91, v0
	v_mov_b32_e32 v92, v0
	v_mov_b32_e32 v93, v0
	v_mov_b32_e32 v94, v0
	v_mov_b32_e32 v95, v0
	v_mov_b32_e32 v104, v0
	v_mov_b32_e32 v105, v0
	v_mov_b32_e32 v106, v0
	v_mov_b32_e32 v107, v0
	v_mov_b32_e32 v108, v0
	v_mov_b32_e32 v109, v0
	v_mov_b32_e32 v110, v0
	v_mov_b32_e32 v111, v0
	v_mov_b32_e32 v120, v0
	v_mov_b32_e32 v121, v0
	v_mov_b32_e32 v122, v0
	v_mov_b32_e32 v123, v0
	v_mov_b32_e32 v124, v0
	v_mov_b32_e32 v125, v0
	v_mov_b32_e32 v126, v0
	v_mov_b32_e32 v127, v0
	s_add_u32 s42, s26, 0xfffc0080
	s_addc_u32 s43, s27, -1
	s_add_i32 s76, 0, 0x10000
	s_cmp_eq_u32 s95, 12
	s_cselect_b32 s47, s41, s43
	s_cselect_b32 s46, s92, s42
	s_cselect_b32 s43, s39, s94
	s_cselect_b32 s42, s93, vcc_lo
	s_add_i32 s77, 0, 0x14000
.LBB0_426:
	v_add_u32_e32 v168, s76, v157
	v_add_u32_e32 v184, s77, v157
	ds_read_b128 v[152:155], v168
	ds_read_b128 v[160:163], v168 offset:1024
	ds_read_b128 v[164:167], v168 offset:2048
	ds_read_b128 v[168:171], v168 offset:3072
	ds_read_b128 v[172:175], v184
	ds_read_b128 v[176:179], v184 offset:1024
	ds_read_b128 v[180:183], v184 offset:2048
	ds_read_b128 v[184:187], v184 offset:3072
	v_lshl_add_u64 v[224:225], s[26:27], 0, v[134:135]
	s_add_i32 m0, s48, 0xc000
	ds_read_b128 v[188:191], v159
	ds_read_b128 v[192:195], v159 offset:1024
	ds_read_b128 v[196:199], v159 offset:2048
	ds_read_b128 v[200:203], v159 offset:3072
	ds_read_b128 v[208:211], v159 offset:4096
	ds_read_b128 v[212:215], v159 offset:5120
	ds_read_b128 v[216:219], v159 offset:6144
	ds_read_b128 v[220:223], v159 offset:7168
	global_load_lds_dwordx4 v[224:225], off
	v_lshl_add_u64 v[224:225], s[26:27], 0, v[148:149]
	s_add_i32 m0, s48, 0xe000
	s_nop 0
	global_load_lds_dwordx4 v[224:225], off
	s_waitcnt vmcnt(8)
	s_waitcnt lgkmcnt(0)
	s_barrier
; #define PG8_STAGE(bufoff, gbase, voff) do { _Pragma("unroll") for (int _i = 0; _i < 2; ++_i) \
;         __builtin_amdgcn_global_load_lds((const unsigned*)((const char*)(gbase) + (voff)[_i]), (PG8_LAS unsigned*)(lds + (bufoff) + ldsw + _i * 8192), 16, 0, 0); } while (0)
; #define PG8_LDA(dst, b, h) do { _Pragma("unroll") for (int m = 0; m < 4; ++m) _Pragma("unroll") for (int k = 0; k < 2; ++k) dst[m][k] = *(const PG8_LAS bf16x8*)(lds + PG8_SA(b, h) + aoff + m * 2048 + k * 1024); } while (0)
; #define PG8_LDB(dst, b, h) do { _Pragma("unroll") for (int n = 0; n < 2; ++n) _Pragma("unroll") for (int k = 0; k < 2; ++k) dst[n][k] = *(const PG8_LAS bf16x8*)(lds + PG8_SB(b, h) + boff + n * 2048 + k * 1024); } while (0)
; #define PG8_MMA(ai, bj, At, Bt) do { __builtin_amdgcn_s_setprio(1); _Pragma("unroll") for (int m = 0; m < 4; ++m) _Pragma("unroll") for (int n = 0; n < 2; ++n) _Pragma("unroll") for (int k = 0; k < 2; ++k) \
;         acc[ai][bj][m][n] = __builtin_amdgcn_mfma_f32_16x16x32_bf16(Bt[n][k], At[m][k], acc[ai][bj][m][n], 0, 0, 0); __builtin_amdgcn_s_setprio(0); } while (0)
; #define PG8_WAIT_V(n) asm volatile("s_waitcnt vmcnt(" #n ")" ::: "memory")
; #define PG8_WAIT_L(n) asm volatile("s_waitcnt lgkmcnt(" #n ")" ::: "memory")
; #define PG8_BAR __builtin_amdgcn_s_barrier()
; #define PG8_SCHED __builtin_amdgcn_sched_barrier(0)
; template <class Epi, class Sched, bool ALIGN_EPI = false, bool SP2 = false>
; __device__ __forceinline__ void gemm_phase(PG8_LAS unsigned char* lds, const Gemm g, const Sched& S, const Epi& E) {
;     ...
;             PG8_LDB(B0, 0, 0); PG8_LDB(B1, 0, 1); PG8_SCHED; PG8_LDA(At, 0, 0); PG8_STAGE(PG8_SA(1, 1), a1 + hstep, voffA);
;             PG8_WAIT_V(8); PG8_WAIT_L(0); PG8_BAR; PG8_MMA(0, 0, At, B0); PG8_MMA(0, 1, At, B1); PG8_BAR; PG8_SCHED;
;             PG8_LDA(At, 0, 1); PG8_STAGE(PG8_SB(0, 0), b2, voffB); PG8_STAGE(PG8_SB(0, 1), b2 + hstep, voffB); PG8_STAGE(PG8_SA(0, 0), a2, voffA);
;             PG8_WAIT_V(8); PG8_WAIT_L(0); PG8_BAR; PG8_MMA(1, 0, At, B0); PG8_MMA(1, 1, At, B1); PG8_BAR; PG8_SCHED;
	s_setprio 1
	s_waitcnt lgkmcnt(0)
	v_mfma_f32_16x16x32_bf16 v[124:127], v[152:155], v[188:191], v[124:127]
	v_mfma_f32_16x16x32_bf16 v[120:123], v[164:167], v[188:191], v[120:123]
	v_mfma_f32_16x16x32_bf16 v[108:111], v[152:155], v[196:199], v[108:111]
	v_mfma_f32_16x16x32_bf16 v[104:107], v[164:167], v[196:199], v[104:107]
	v_mfma_f32_16x16x32_bf16 v[92:95], v[152:155], v[208:211], v[92:95]
	v_mfma_f32_16x16x32_bf16 v[88:91], v[164:167], v[208:211], v[88:91]
	v_mfma_f32_16x16x32_bf16 v[76:79], v[152:155], v[216:219], v[76:79]
	v_mfma_f32_16x16x32_bf16 v[72:75], v[164:167], v[216:219], v[72:75]
	v_mfma_f32_16x16x32_bf16 v[124:127], v[160:163], v[192:195], v[124:127]
	v_mfma_f32_16x16x32_bf16 v[120:123], v[168:171], v[192:195], v[120:123]
	v_mfma_f32_16x16x32_bf16 v[108:111], v[160:163], v[200:203], v[108:111]
	v_mfma_f32_16x16x32_bf16 v[104:107], v[168:171], v[200:203], v[104:107]
	v_mfma_f32_16x16x32_bf16 v[92:95], v[160:163], v[212:215], v[92:95]
	v_mfma_f32_16x16x32_bf16 v[88:91], v[168:171], v[212:215], v[88:91]
	v_mfma_f32_16x16x32_bf16 v[76:79], v[160:163], v[220:223], v[76:79]
	v_mfma_f32_16x16x32_bf16 v[72:75], v[168:171], v[220:223], v[72:75]
	s_setprio 0
	s_setprio 1
	v_mfma_f32_16x16x32_bf16 v[116:119], v[172:175], v[188:191], v[116:119]
	v_mfma_f32_16x16x32_bf16 v[112:115], v[180:183], v[188:191], v[112:115]
	v_mfma_f32_16x16x32_bf16 v[100:103], v[172:175], v[196:199], v[100:103]
	v_mfma_f32_16x16x32_bf16 v[96:99], v[180:183], v[196:199], v[96:99]
	v_mfma_f32_16x16x32_bf16 v[84:87], v[172:175], v[208:211], v[84:87]
	v_mfma_f32_16x16x32_bf16 v[80:83], v[180:183], v[208:211], v[80:83]
	v_mfma_f32_16x16x32_bf16 v[68:71], v[172:175], v[216:219], v[68:71]
	v_mfma_f32_16x16x32_bf16 v[64:67], v[180:183], v[216:219], v[64:67]
	v_mfma_f32_16x16x32_bf16 v[116:119], v[176:179], v[192:195], v[116:119]
	v_mfma_f32_16x16x32_bf16 v[112:115], v[184:187], v[192:195], v[112:115]
	v_mfma_f32_16x16x32_bf16 v[100:103], v[176:179], v[200:203], v[100:103]
	v_mfma_f32_16x16x32_bf16 v[96:99], v[184:187], v[200:203], v[96:99]
	v_mfma_f32_16x16x32_bf16 v[84:87], v[176:179], v[212:215], v[84:87]
	v_mfma_f32_16x16x32_bf16 v[80:83], v[184:187], v[212:215], v[80:83]
	v_mfma_f32_16x16x32_bf16 v[68:71], v[176:179], v[220:223], v[68:71]
	v_mfma_f32_16x16x32_bf16 v[64:67], v[184:187], v[220:223], v[64:67]
	s_setprio 0
	s_barrier
	s_add_i32 s76, s76, s54
	v_lshl_add_u64 v[224:225], s[42:43], 0, v[138:139]
	s_mov_b32 m0, s76
	ds_read_b128 v[188:191], v159 offset:16384
	ds_read_b128 v[192:195], v159 offset:17408
	ds_read_b128 v[196:199], v159 offset:18432
	ds_read_b128 v[200:203], v159 offset:19456
	ds_read_b128 v[208:211], v159 offset:20480
	ds_read_b128 v[212:215], v159 offset:21504
	ds_read_b128 v[216:219], v159 offset:22528
	ds_read_b128 v[220:223], v159 offset:23552
	global_load_lds_dwordx4 v[224:225], off
	s_add_i32 m0, s76, 0x2000
	s_add_u32 s96, s42, 0x40000
	v_lshl_add_u64 v[226:227], s[42:43], 0, v[128:129]
	s_addc_u32 s97, s43, 0
	s_add_i32 s76, s77, s54
	global_load_lds_dwordx4 v[226:227], off
	v_lshl_add_u64 v[228:229], s[96:97], 0, v[138:139]
	s_mov_b32 m0, s76
	v_lshl_add_u64 v[230:231], s[46:47], 0, v[130:131]
	global_load_lds_dwordx4 v[228:229], off
	v_lshl_add_u64 v[228:229], s[96:97], 0, v[128:129]
	s_add_i32 m0, s76, 0x2000
	s_nop 0
	global_load_lds_dwordx4 v[228:229], off
	v_lshl_add_u64 v[228:229], s[46:47], 0, v[132:133]
	s_mov_b32 m0, s48
	s_nop 0
	global_load_lds_dwordx4 v[228:229], off
	s_mov_b32 m0, s0
	s_nop 0
	global_load_lds_dwordx4 v[230:231], off
	s_waitcnt vmcnt(8)
	s_waitcnt lgkmcnt(0)
	s_barrier
	s_setprio 1
	s_waitcnt lgkmcnt(0)
	v_mfma_f32_16x16x32_bf16 v[60:63], v[152:155], v[188:191], v[60:63]
	v_mfma_f32_16x16x32_bf16 v[56:59], v[164:167], v[188:191], v[56:59]
	v_mfma_f32_16x16x32_bf16 v[44:47], v[152:155], v[196:199], v[44:47]
	v_mfma_f32_16x16x32_bf16 v[40:43], v[164:167], v[196:199], v[40:43]
	v_mfma_f32_16x16x32_bf16 v[28:31], v[152:155], v[208:211], v[28:31]
	v_mfma_f32_16x16x32_bf16 v[24:27], v[164:167], v[208:211], v[24:27]
	v_mfma_f32_16x16x32_bf16 v[12:15], v[152:155], v[216:219], v[12:15]
	v_mfma_f32_16x16x32_bf16 v[8:11], v[164:167], v[216:219], v[8:11]
	v_mfma_f32_16x16x32_bf16 v[60:63], v[160:163], v[192:195], v[60:63]
	v_mfma_f32_16x16x32_bf16 v[56:59], v[168:171], v[192:195], v[56:59]
	v_mfma_f32_16x16x32_bf16 v[44:47], v[160:163], v[200:203], v[44:47]
	v_mfma_f32_16x16x32_bf16 v[40:43], v[168:171], v[200:203], v[40:43]
	v_mfma_f32_16x16x32_bf16 v[28:31], v[160:163], v[212:215], v[28:31]
	v_mfma_f32_16x16x32_bf16 v[24:27], v[168:171], v[212:215], v[24:27]
	v_mfma_f32_16x16x32_bf16 v[12:15], v[160:163], v[220:223], v[12:15]
	v_mfma_f32_16x16x32_bf16 v[8:11], v[168:171], v[220:223], v[8:11]
	s_setprio 0
	s_setprio 1
	v_mfma_f32_16x16x32_bf16 v[52:55], v[172:175], v[188:191], v[52:55]
	v_mfma_f32_16x16x32_bf16 v[48:51], v[180:183], v[188:191], v[48:51]
	v_mfma_f32_16x16x32_bf16 v[36:39], v[172:175], v[196:199], v[36:39]
	v_mfma_f32_16x16x32_bf16 v[32:35], v[180:183], v[196:199], v[32:35]
	v_mfma_f32_16x16x32_bf16 v[20:23], v[172:175], v[208:211], v[20:23]
	v_mfma_f32_16x16x32_bf16 v[16:19], v[180:183], v[208:211], v[16:19]
	v_mfma_f32_16x16x32_bf16 v[4:7], v[172:175], v[216:219], v[4:7]
	v_mfma_f32_16x16x32_bf16 v[0:3], v[180:183], v[216:219], v[0:3]
	v_mfma_f32_16x16x32_bf16 v[52:55], v[176:179], v[192:195], v[52:55]
	v_mfma_f32_16x16x32_bf16 v[48:51], v[184:187], v[192:195], v[48:51]
	v_mfma_f32_16x16x32_bf16 v[36:39], v[176:179], v[200:203], v[36:39]
	v_mfma_f32_16x16x32_bf16 v[32:35], v[184:187], v[200:203], v[32:35]
	v_mfma_f32_16x16x32_bf16 v[20:23], v[176:179], v[212:215], v[20:23]
	v_mfma_f32_16x16x32_bf16 v[16:19], v[184:187], v[212:215], v[16:19]
	v_mfma_f32_16x16x32_bf16 v[4:7], v[176:179], v[220:223], v[4:7]
	v_mfma_f32_16x16x32_bf16 v[0:3], v[184:187], v[220:223], v[0:3]
	s_setprio 0
	s_barrier
; #define PG8_STAGE(bufoff, gbase, voff) do { _Pragma("unroll") for (int _i = 0; _i < 2; ++_i) \
;         __builtin_amdgcn_global_load_lds((const unsigned*)((const char*)(gbase) + (voff)[_i]), (PG8_LAS unsigned*)(lds + (bufoff) + ldsw + _i * 8192), 16, 0, 0); } while (0)
; #define PG8_LDA(dst, b, h) do { _Pragma("unroll") for (int m = 0; m < 4; ++m) _Pragma("unroll") for (int k = 0; k < 2; ++k) dst[m][k] = *(const PG8_LAS bf16x8*)(lds + PG8_SA(b, h) + aoff + m * 2048 + k * 1024); } while (0)
; #define PG8_LDB(dst, b, h) do { _Pragma("unroll") for (int n = 0; n < 2; ++n) _Pragma("unroll") for (int k = 0; k < 2; ++k) dst[n][k] = *(const PG8_LAS bf16x8*)(lds + PG8_SB(b, h) + boff + n * 2048 + k * 1024); } while (0)
; #define PG8_MMA(ai, bj, At, Bt) do { __builtin_amdgcn_s_setprio(1); _Pragma("unroll") for (int m = 0; m < 4; ++m) _Pragma("unroll") for (int n = 0; n < 2; ++n) _Pragma("unroll") for (int k = 0; k < 2; ++k) \
;         acc[ai][bj][m][n] = __builtin_amdgcn_mfma_f32_16x16x32_bf16(Bt[n][k], At[m][k], acc[ai][bj][m][n], 0, 0, 0); __builtin_amdgcn_s_setprio(0); } while (0)
; #define PG8_WAIT_V(n) asm volatile("s_waitcnt vmcnt(" #n ")" ::: "memory")
; #define PG8_WAIT_L(n) asm volatile("s_waitcnt lgkmcnt(" #n ")" ::: "memory")
; #define PG8_BAR __builtin_amdgcn_s_barrier()
; #define PG8_SCHED __builtin_amdgcn_sched_barrier(0)
; template <class Epi, class Sched, bool ALIGN_EPI = false, bool SP2 = false>
; __device__ __forceinline__ void gemm_phase(PG8_LAS unsigned char* lds, const Gemm g, const Sched& S, const Epi& E) {
;     ...
;             PG8_LDB(B0, 1, 0); PG8_LDB(B1, 1, 1); PG8_SCHED; PG8_LDA(At, 1, 0); PG8_STAGE(PG8_SA(0, 1), a2 + hstep, voffA);
;             PG8_WAIT_V(8); PG8_WAIT_L(0); PG8_BAR; PG8_MMA(0, 0, At, B0); PG8_MMA(0, 1, At, B1); PG8_BAR; PG8_SCHED;
	s_add_i32 s76, 0, 0x18000
	s_add_i32 s77, 0, 0x1c000
	v_add_u32_e32 v168, s76, v157
	v_add_u32_e32 v184, s77, v157
	ds_read_b128 v[152:155], v168
	ds_read_b128 v[160:163], v168 offset:1024
	ds_read_b128 v[164:167], v168 offset:2048
	ds_read_b128 v[168:171], v168 offset:3072
	ds_read_b128 v[172:175], v184
	ds_read_b128 v[176:179], v184 offset:1024
	ds_read_b128 v[180:183], v184 offset:2048
	ds_read_b128 v[184:187], v184 offset:3072
	s_add_u32 s46, s46, 0x40000
	s_addc_u32 s47, s47, 0
	s_mov_b32 m0, s1
	v_lshl_add_u64 v[232:233], s[46:47], 0, v[132:133]
	ds_read_b128 v[188:191], v159 offset:32768
	ds_read_b128 v[192:195], v159 offset:33792
	ds_read_b128 v[196:199], v159 offset:34816
	ds_read_b128 v[200:203], v159 offset:35840
	ds_read_b128 v[208:211], v159 offset:36864
	ds_read_b128 v[212:215], v159 offset:37888
	ds_read_b128 v[216:219], v159 offset:38912
	ds_read_b128 v[220:223], v159 offset:39936
	global_load_lds_dwordx4 v[232:233], off
	v_lshl_add_u64 v[232:233], s[46:47], 0, v[130:131]
	s_mov_b32 m0, s22
	s_nop 0
	global_load_lds_dwordx4 v[232:233], off
	s_waitcnt vmcnt(8)
	s_waitcnt lgkmcnt(0)
	s_barrier
	s_setprio 1
	s_waitcnt lgkmcnt(0)
	v_mfma_f32_16x16x32_bf16 v[124:127], v[152:155], v[188:191], v[124:127]
	v_mfma_f32_16x16x32_bf16 v[120:123], v[164:167], v[188:191], v[120:123]
	v_mfma_f32_16x16x32_bf16 v[108:111], v[152:155], v[196:199], v[108:111]
	v_mfma_f32_16x16x32_bf16 v[104:107], v[164:167], v[196:199], v[104:107]
	v_mfma_f32_16x16x32_bf16 v[92:95], v[152:155], v[208:211], v[92:95]
	v_mfma_f32_16x16x32_bf16 v[88:91], v[164:167], v[208:211], v[88:91]
	v_mfma_f32_16x16x32_bf16 v[76:79], v[152:155], v[216:219], v[76:79]
	v_mfma_f32_16x16x32_bf16 v[72:75], v[164:167], v[216:219], v[72:75]
	v_mfma_f32_16x16x32_bf16 v[124:127], v[160:163], v[192:195], v[124:127]
	v_mfma_f32_16x16x32_bf16 v[120:123], v[168:171], v[192:195], v[120:123]
	v_mfma_f32_16x16x32_bf16 v[108:111], v[160:163], v[200:203], v[108:111]
	v_mfma_f32_16x16x32_bf16 v[104:107], v[168:171], v[200:203], v[104:107]
	v_mfma_f32_16x16x32_bf16 v[92:95], v[160:163], v[212:215], v[92:95]
	v_mfma_f32_16x16x32_bf16 v[88:91], v[168:171], v[212:215], v[88:91]
	v_mfma_f32_16x16x32_bf16 v[76:79], v[160:163], v[220:223], v[76:79]
	v_mfma_f32_16x16x32_bf16 v[72:75], v[168:171], v[220:223], v[72:75]
	s_setprio 0
	s_setprio 1
	v_mfma_f32_16x16x32_bf16 v[116:119], v[172:175], v[188:191], v[116:119]
	v_mfma_f32_16x16x32_bf16 v[112:115], v[180:183], v[188:191], v[112:115]
	v_mfma_f32_16x16x32_bf16 v[100:103], v[172:175], v[196:199], v[100:103]
	v_mfma_f32_16x16x32_bf16 v[96:99], v[180:183], v[196:199], v[96:99]
	v_mfma_f32_16x16x32_bf16 v[84:87], v[172:175], v[208:211], v[84:87]
	v_mfma_f32_16x16x32_bf16 v[80:83], v[180:183], v[208:211], v[80:83]
	v_mfma_f32_16x16x32_bf16 v[68:71], v[172:175], v[216:219], v[68:71]
	v_mfma_f32_16x16x32_bf16 v[64:67], v[180:183], v[216:219], v[64:67]
	v_mfma_f32_16x16x32_bf16 v[116:119], v[176:179], v[192:195], v[116:119]
	v_mfma_f32_16x16x32_bf16 v[112:115], v[184:187], v[192:195], v[112:115]
	v_mfma_f32_16x16x32_bf16 v[100:103], v[176:179], v[200:203], v[100:103]
	v_mfma_f32_16x16x32_bf16 v[96:99], v[184:187], v[200:203], v[96:99]
	v_mfma_f32_16x16x32_bf16 v[84:87], v[176:179], v[212:215], v[84:87]
	v_mfma_f32_16x16x32_bf16 v[80:83], v[184:187], v[212:215], v[80:83]
	v_mfma_f32_16x16x32_bf16 v[68:71], v[176:179], v[220:223], v[68:71]
	v_mfma_f32_16x16x32_bf16 v[64:67], v[184:187], v[220:223], v[64:67]
	s_setprio 0
	s_barrier
; #define PG8_STAGE(bufoff, gbase, voff) do { _Pragma("unroll") for (int _i = 0; _i < 2; ++_i) \
;         __builtin_amdgcn_global_load_lds((const unsigned*)((const char*)(gbase) + (voff)[_i]), (PG8_LAS unsigned*)(lds + (bufoff) + ldsw + _i * 8192), 16, 0, 0); } while (0)
; #define PG8_LDA(dst, b, h) do { _Pragma("unroll") for (int m = 0; m < 4; ++m) _Pragma("unroll") for (int k = 0; k < 2; ++k) dst[m][k] = *(const PG8_LAS bf16x8*)(lds + PG8_SA(b, h) + aoff + m * 2048 + k * 1024); } while (0)
; #define PG8_MMA(ai, bj, At, Bt) do { __builtin_amdgcn_s_setprio(1); _Pragma("unroll") for (int m = 0; m < 4; ++m) _Pragma("unroll") for (int n = 0; n < 2; ++n) _Pragma("unroll") for (int k = 0; k < 2; ++k) \
;         acc[ai][bj][m][n] = __builtin_amdgcn_mfma_f32_16x16x32_bf16(Bt[n][k], At[m][k], acc[ai][bj][m][n], 0, 0, 0); __builtin_amdgcn_s_setprio(0); } while (0)
; #define PG8_WAIT_V(n) asm volatile("s_waitcnt vmcnt(" #n ")" ::: "memory")
; #define PG8_WAIT_L(n) asm volatile("s_waitcnt lgkmcnt(" #n ")" ::: "memory")
; #define PG8_BAR __builtin_amdgcn_s_barrier()
; #define PG8_SCHED __builtin_amdgcn_sched_barrier(0)
; template <class Epi, class Sched, bool ALIGN_EPI = false, bool SP2 = false>
; __device__ __forceinline__ void gemm_phase(PG8_LAS unsigned char* lds, const Gemm g, const Sched& S, const Epi& E) {
;     ...
;         for (int t = 0; t < nt; t += 2) {
;             const bool last = (t == nt - 2);
;             const char* a1 = cA + (size_t)(t + 1) * kstep;
;             const char* a2 = last ? nA : cA + (size_t)(t + 2) * kstep; const char* b2 = last ? nB : cB + (size_t)(t + 2) * kstep;
;     ...
;             PG8_LDA(At, 1, 1); PG8_STAGE(PG8_SB(1, 0), b3, voffB); PG8_STAGE(PG8_SB(1, 1), b3 + hstep, voffB); PG8_STAGE(PG8_SA(1, 0), a3, voffA);
;             PG8_WAIT_V(8); PG8_WAIT_L(0); PG8_BAR; PG8_MMA(1, 0, At, B0); PG8_MMA(1, 1, At, B1); PG8_BAR; PG8_SCHED;
	s_add_i32 s46, s76, s54
	v_lshl_add_u64 v[224:225], v[224:225], 0, s[34:35]
	s_mov_b32 m0, s46
	ds_read_b128 v[188:191], v159 offset:49152
	ds_read_b128 v[192:195], v159 offset:50176
	ds_read_b128 v[196:199], v159 offset:51200
	ds_read_b128 v[200:203], v159 offset:52224
	ds_read_b128 v[208:211], v159 offset:53248
	ds_read_b128 v[212:215], v159 offset:54272
	ds_read_b128 v[216:219], v159 offset:55296
	ds_read_b128 v[220:223], v159 offset:56320
	global_load_lds_dwordx4 v[224:225], off
	s_add_i32 m0, s46, 0x2000
	s_add_u32 s42, s42, 0x40080
	v_lshl_add_u64 v[224:225], v[226:227], 0, s[34:35]
	s_addc_u32 s43, s43, 0
	s_add_i32 s46, s77, s54
	global_load_lds_dwordx4 v[224:225], off
	v_lshl_add_u64 v[224:225], s[42:43], 0, v[138:139]
	s_mov_b32 m0, s46
	s_nop 0
	global_load_lds_dwordx4 v[224:225], off
	v_lshl_add_u64 v[224:225], s[42:43], 0, v[128:129]
	s_add_i32 m0, s46, 0x2000
	s_nop 0
	global_load_lds_dwordx4 v[224:225], off
	v_lshl_add_u64 v[224:225], v[228:229], 0, s[34:35]
	s_mov_b32 m0, s23
	s_nop 0
	global_load_lds_dwordx4 v[224:225], off
	v_lshl_add_u64 v[224:225], v[230:231], 0, s[34:35]
	s_mov_b32 m0, s58
	s_nop 0
	global_load_lds_dwordx4 v[224:225], off
	s_waitcnt vmcnt(8)
	s_waitcnt lgkmcnt(0)
	s_barrier
	s_setprio 1
	s_waitcnt lgkmcnt(0)
	v_mfma_f32_16x16x32_bf16 v[60:63], v[152:155], v[188:191], v[60:63]
	v_mfma_f32_16x16x32_bf16 v[56:59], v[164:167], v[188:191], v[56:59]
	v_mfma_f32_16x16x32_bf16 v[44:47], v[152:155], v[196:199], v[44:47]
	v_mfma_f32_16x16x32_bf16 v[40:43], v[164:167], v[196:199], v[40:43]
	v_mfma_f32_16x16x32_bf16 v[28:31], v[152:155], v[208:211], v[28:31]
	v_mfma_f32_16x16x32_bf16 v[24:27], v[164:167], v[208:211], v[24:27]
	v_mfma_f32_16x16x32_bf16 v[12:15], v[152:155], v[216:219], v[12:15]
	v_mfma_f32_16x16x32_bf16 v[8:11], v[164:167], v[216:219], v[8:11]
	v_mfma_f32_16x16x32_bf16 v[60:63], v[160:163], v[192:195], v[60:63]
	v_mfma_f32_16x16x32_bf16 v[56:59], v[168:171], v[192:195], v[56:59]
	v_mfma_f32_16x16x32_bf16 v[44:47], v[160:163], v[200:203], v[44:47]
	v_mfma_f32_16x16x32_bf16 v[40:43], v[168:171], v[200:203], v[40:43]
	v_mfma_f32_16x16x32_bf16 v[28:31], v[160:163], v[212:215], v[28:31]
	v_mfma_f32_16x16x32_bf16 v[24:27], v[168:171], v[212:215], v[24:27]
	v_mfma_f32_16x16x32_bf16 v[12:15], v[160:163], v[220:223], v[12:15]
	v_mfma_f32_16x16x32_bf16 v[8:11], v[168:171], v[220:223], v[8:11]
	s_setprio 0
	s_setprio 1
	v_mfma_f32_16x16x32_bf16 v[52:55], v[172:175], v[188:191], v[52:55]
	s_add_i32 s95, s95, 2
	s_add_u32 s26, s26, 0x100
	s_addc_u32 s27, s27, 0
	v_mfma_f32_16x16x32_bf16 v[48:51], v[180:183], v[188:191], v[48:51]
	s_add_u32 vcc_lo, vcc_lo, 0x100
	s_addc_u32 s94, s94, 0
	s_add_u32 s42, s26, 0xfffc0080
	v_mfma_f32_16x16x32_bf16 v[36:39], v[172:175], v[196:199], v[36:39]
	s_addc_u32 s43, s27, -1
	s_add_i32 s76, 0, 0x10000
	s_cmp_eq_u32 s95, 12
	v_mfma_f32_16x16x32_bf16 v[32:35], v[180:183], v[196:199], v[32:35]
	s_cselect_b32 s47, s41, s43
	s_cselect_b32 s46, s92, s42
	s_cselect_b32 s43, s39, s94
	v_mfma_f32_16x16x32_bf16 v[20:23], v[172:175], v[208:211], v[20:23]
	s_cselect_b32 s42, s93, vcc_lo
	s_add_i32 s77, 0, 0x14000
	s_cmp_gt_u32 s95, 13
	v_mfma_f32_16x16x32_bf16 v[16:19], v[180:183], v[208:211], v[16:19]
	v_mfma_f32_16x16x32_bf16 v[4:7], v[172:175], v[216:219], v[4:7]
	v_mfma_f32_16x16x32_bf16 v[0:3], v[180:183], v[216:219], v[0:3]
	v_mfma_f32_16x16x32_bf16 v[52:55], v[176:179], v[192:195], v[52:55]
	v_mfma_f32_16x16x32_bf16 v[48:51], v[184:187], v[192:195], v[48:51]
	v_mfma_f32_16x16x32_bf16 v[36:39], v[176:179], v[200:203], v[36:39]
	v_mfma_f32_16x16x32_bf16 v[32:35], v[184:187], v[200:203], v[32:35]
	v_mfma_f32_16x16x32_bf16 v[20:23], v[176:179], v[212:215], v[20:23]
	v_mfma_f32_16x16x32_bf16 v[16:19], v[184:187], v[212:215], v[16:19]
	v_mfma_f32_16x16x32_bf16 v[4:7], v[176:179], v[220:223], v[4:7]
	v_mfma_f32_16x16x32_bf16 v[0:3], v[184:187], v[220:223], v[0:3]
	s_setprio 0
	s_barrier
	s_cbranch_scc0 .LBB0_426
	s_and_b64 vcc, exec, s[28:29]
	s_cbranch_vccz .LBB0_429
	s_barrier

; template <class Epi, class Sched, bool ALIGN_EPI = false, bool SP2 = false>
; __device__ __forceinline__ void gemm_phase(PG8_LAS unsigned char* lds, const Gemm g, const Sched& S, const Epi& E) {
;     ...
;         const bool has_next = S.next(ui + 1, nxt);
;         const char* nA = has_next ? (const char*)g.A + (size_t)nxt.pm * tstep : cA; const char* nB = has_next ? (const char*)g.Bt + (size_t)nxt.pn * tstep : cB;
;         for (int t = 0; t < nt; t += 2) {
;             const bool last = (t == nt - 2);
;             const char* a1 = cA + (size_t)(t + 1) * kstep;
;             const char* a2 = last ? nA : cA + (size_t)(t + 2) * kstep; const char* b2 = last ? nB : cB + (size_t)(t + 2) * kstep;
;     ...
; #pragma unroll
;         for (int a = 0; a < 2; ++a)
; #pragma unroll
;             for (int b = 0; b < 2; ++b)
; #pragma unroll
;                 for (int m = 0; m < 4; ++m)
; #pragma unroll
;                     for (int n = 0; n < 2; ++n) acc[a][b][m][n] = (f32x4){0.f, 0.f, 0.f, 0.f};
;         cur = nxt; cA = nA; cB = nB; ++ui;
.LBB0_1058:
	s_ashr_i32 s47, s46, 31
	s_lshl_b64 s[36:37], s[46:47], 19
	s_add_u32 s48, s80, s36
	s_addc_u32 s49, s81, s37
	s_and_b64 s[36:37], s[40:41], exec
	s_cselect_b32 s47, s49, s25
	s_cselect_b32 vcc_lo, s48, s24
	s_ashr_i32 s29, s28, 31
	s_lshl_b64 s[36:37], s[28:29], 19
	s_add_u32 s52, s58, s36
	s_addc_u32 s53, s59, s37
	s_and_b64 s[36:37], s[40:41], exec
	s_cselect_b32 s29, s53, s27
	s_cselect_b32 vcc_hi, s52, s26
	s_add_u32 s24, s24, 0x40080
	s_addc_u32 s25, s25, 0
	s_add_u32 s36, s26, 0x100
	v_mov_b32_e32 v0, 0
	s_addc_u32 s37, s27, 0
	s_mov_b32 s94, -2
	s_waitcnt lgkmcnt(0)
	v_mov_b32_e32 v1, v0
	v_mov_b32_e32 v2, v0
	v_mov_b32_e32 v3, v0
	v_mov_b32_e32 v4, v0
	v_mov_b32_e32 v5, v0
	v_mov_b32_e32 v6, v0
	v_mov_b32_e32 v7, v0
	v_mov_b32_e32 v16, v0
	v_mov_b32_e32 v17, v0
	v_mov_b32_e32 v18, v0
	v_mov_b32_e32 v19, v0
	v_mov_b32_e32 v20, v0
	v_mov_b32_e32 v21, v0
	v_mov_b32_e32 v22, v0
	v_mov_b32_e32 v23, v0
	s_waitcnt vmcnt(0)
	v_mov_b32_e32 v32, v0
	v_mov_b32_e32 v33, v0
	v_mov_b32_e32 v34, v0
	v_mov_b32_e32 v35, v0
	v_mov_b32_e32 v36, v0
	v_mov_b32_e32 v37, v0
	v_mov_b32_e32 v38, v0
	v_mov_b32_e32 v39, v0
	v_mov_b32_e32 v48, v0
	v_mov_b32_e32 v49, v0
	v_mov_b32_e32 v50, v0
	v_mov_b32_e32 v51, v0
	v_mov_b32_e32 v52, v0
	v_mov_b32_e32 v53, v0
	v_mov_b32_e32 v54, v0
	v_mov_b32_e32 v55, v0
	v_mov_b32_e32 v8, v0
	v_mov_b32_e32 v9, v0
	v_mov_b32_e32 v10, v0
	v_mov_b32_e32 v11, v0
	v_mov_b32_e32 v12, v0
	v_mov_b32_e32 v13, v0
	v_mov_b32_e32 v14, v0
	v_mov_b32_e32 v15, v0
	v_mov_b32_e32 v24, v0
	v_mov_b32_e32 v25, v0
	v_mov_b32_e32 v26, v0
	v_mov_b32_e32 v27, v0
	v_mov_b32_e32 v28, v0
	v_mov_b32_e32 v29, v0
	v_mov_b32_e32 v30, v0
	v_mov_b32_e32 v31, v0
	v_mov_b32_e32 v40, v0
	v_mov_b32_e32 v41, v0
	v_mov_b32_e32 v42, v0
	v_mov_b32_e32 v43, v0
	v_mov_b32_e32 v44, v0
	v_mov_b32_e32 v45, v0
	v_mov_b32_e32 v46, v0
	v_mov_b32_e32 v47, v0
	v_mov_b32_e32 v56, v0
	v_mov_b32_e32 v57, v0
	v_mov_b32_e32 v58, v0
	v_mov_b32_e32 v59, v0
	v_mov_b32_e32 v60, v0
	v_mov_b32_e32 v61, v0
	v_mov_b32_e32 v62, v0
	v_mov_b32_e32 v63, v0
	v_mov_b32_e32 v64, v0
	v_mov_b32_e32 v65, v0
	v_mov_b32_e32 v66, v0
	v_mov_b32_e32 v67, v0
	v_mov_b32_e32 v68, v0
	v_mov_b32_e32 v69, v0
	v_mov_b32_e32 v70, v0
	v_mov_b32_e32 v71, v0
	v_mov_b32_e32 v80, v0
	v_mov_b32_e32 v81, v0
	v_mov_b32_e32 v82, v0
	v_mov_b32_e32 v83, v0
	v_mov_b32_e32 v84, v0
	v_mov_b32_e32 v85, v0
	v_mov_b32_e32 v86, v0
	v_mov_b32_e32 v87, v0
	v_mov_b32_e32 v96, v0
	v_mov_b32_e32 v97, v0
	v_mov_b32_e32 v98, v0
	v_mov_b32_e32 v99, v0
	v_mov_b32_e32 v100, v0
	v_mov_b32_e32 v101, v0
	v_mov_b32_e32 v102, v0
	v_mov_b32_e32 v103, v0
	v_mov_b32_e32 v112, v0
	v_mov_b32_e32 v113, v0
	v_mov_b32_e32 v114, v0
	v_mov_b32_e32 v115, v0
	v_mov_b32_e32 v116, v0
	v_mov_b32_e32 v117, v0
	v_mov_b32_e32 v118, v0
	v_mov_b32_e32 v119, v0
	v_mov_b32_e32 v72, v0
	v_mov_b32_e32 v73, v0
	v_mov_b32_e32 v74, v0
	v_mov_b32_e32 v75, v0
	v_mov_b32_e32 v76, v0
	v_mov_b32_e32 v77, v0
	v_mov_b32_e32 v78, v0
	v_mov_b32_e32 v79, v0
	v_mov_b32_e32 v88, v0
	v_mov_b32_e32 v89, v0
	v_mov_b32_e32 v90, v0
	v_mov_b32_e32 v91, v0
	v_mov_b32_e32 v92, v0
	v_mov_b32_e32 v93, v0
	v_mov_b32_e32 v94, v0
	v_mov_b32_e32 v95, v0
	v_mov_b32_e32 v104, v0
	v_mov_b32_e32 v105, v0
	v_mov_b32_e32 v106, v0
	v_mov_b32_e32 v107, v0
	v_mov_b32_e32 v108, v0
	v_mov_b32_e32 v109, v0
	v_mov_b32_e32 v110, v0
	v_mov_b32_e32 v111, v0
	v_mov_b32_e32 v120, v0
	v_mov_b32_e32 v121, v0
	v_mov_b32_e32 v122, v0
	v_mov_b32_e32 v123, v0
	v_mov_b32_e32 v124, v0
	v_mov_b32_e32 v125, v0
	v_mov_b32_e32 v126, v0
	v_mov_b32_e32 v127, v0
	s_add_u32 s26, s24, 0xfffc0080
	s_addc_u32 s27, s25, -1
	s_add_i32 s76, 0, 0x10000
	s_cmp_eq_u32 s94, 12
	s_cselect_b32 s43, s47, s27
	s_cselect_b32 s42, vcc_lo, s26
	s_cselect_b32 s27, s29, s37
	s_cselect_b32 s26, vcc_hi, s36
	s_add_i32 s77, 0, 0x14000
.LBB0_1059:
	v_add_u32_e32 v166, s76, v151
	v_add_u32_e32 v182, s77, v151
	ds_read_b128 v[154:157], v166
	ds_read_b128 v[158:161], v166 offset:1024
	ds_read_b128 v[162:165], v166 offset:2048
	ds_read_b128 v[166:169], v166 offset:3072
	ds_read_b128 v[170:173], v182
	ds_read_b128 v[174:177], v182 offset:1024
	ds_read_b128 v[178:181], v182 offset:2048
	ds_read_b128 v[182:185], v182 offset:3072
	v_lshl_add_u64 v[202:203], s[24:25], 0, v[134:135]
	s_add_i32 m0, s30, 0xc000
	ds_read_b128 v[186:189], v153
	ds_read_b128 v[190:193], v153 offset:1024
	ds_read_b128 v[194:197], v153 offset:2048
	ds_read_b128 v[198:201], v153 offset:3072
	ds_read_b128 v[208:211], v153 offset:4096
	ds_read_b128 v[212:215], v153 offset:5120
	ds_read_b128 v[216:219], v153 offset:6144
	ds_read_b128 v[220:223], v153 offset:7168
	global_load_lds_dwordx4 v[202:203], off
	v_lshl_add_u64 v[202:203], s[24:25], 0, v[148:149]
	s_add_i32 m0, s30, 0xe000
	s_nop 0
	global_load_lds_dwordx4 v[202:203], off
	s_waitcnt vmcnt(8)
	s_waitcnt lgkmcnt(0)
	s_barrier
; #define PG8_STAGE(bufoff, gbase, voff) do { _Pragma("unroll") for (int _i = 0; _i < 2; ++_i) \
;         __builtin_amdgcn_global_load_lds((const unsigned*)((const char*)(gbase) + (voff)[_i]), (PG8_LAS unsigned*)(lds + (bufoff) + ldsw + _i * 8192), 16, 0, 0); } while (0)
; #define PG8_LDA(dst, b, h) do { _Pragma("unroll") for (int m = 0; m < 4; ++m) _Pragma("unroll") for (int k = 0; k < 2; ++k) dst[m][k] = *(const PG8_LAS bf16x8*)(lds + PG8_SA(b, h) + aoff + m * 2048 + k * 1024); } while (0)
; #define PG8_LDB(dst, b, h) do { _Pragma("unroll") for (int n = 0; n < 2; ++n) _Pragma("unroll") for (int k = 0; k < 2; ++k) dst[n][k] = *(const PG8_LAS bf16x8*)(lds + PG8_SB(b, h) + boff + n * 2048 + k * 1024); } while (0)
; #define PG8_MMA(ai, bj, At, Bt) do { __builtin_amdgcn_s_setprio(1); _Pragma("unroll") for (int m = 0; m < 4; ++m) _Pragma("unroll") for (int n = 0; n < 2; ++n) _Pragma("unroll") for (int k = 0; k < 2; ++k) \
;         acc[ai][bj][m][n] = __builtin_amdgcn_mfma_f32_16x16x32_bf16(Bt[n][k], At[m][k], acc[ai][bj][m][n], 0, 0, 0); __builtin_amdgcn_s_setprio(0); } while (0)
; #define PG8_WAIT_V(n) asm volatile("s_waitcnt vmcnt(" #n ")" ::: "memory")
; #define PG8_WAIT_L(n) asm volatile("s_waitcnt lgkmcnt(" #n ")" ::: "memory")
; #define PG8_BAR __builtin_amdgcn_s_barrier()
; #define PG8_SCHED __builtin_amdgcn_sched_barrier(0)
; template <class Epi, class Sched, bool ALIGN_EPI = false, bool SP2 = false>
; __device__ __forceinline__ void gemm_phase(PG8_LAS unsigned char* lds, const Gemm g, const Sched& S, const Epi& E) {
;     ...
;             PG8_LDB(B0, 0, 0); PG8_LDB(B1, 0, 1); PG8_SCHED; PG8_LDA(At, 0, 0); PG8_STAGE(PG8_SA(1, 1), a1 + hstep, voffA);
;             PG8_WAIT_V(8); PG8_WAIT_L(0); PG8_BAR; PG8_MMA(0, 0, At, B0); PG8_MMA(0, 1, At, B1); PG8_BAR; PG8_SCHED;
;             PG8_LDA(At, 0, 1); PG8_STAGE(PG8_SB(0, 0), b2, voffB); PG8_STAGE(PG8_SB(0, 1), b2 + hstep, voffB); PG8_STAGE(PG8_SA(0, 0), a2, voffA);
;             PG8_WAIT_V(8); PG8_WAIT_L(0); PG8_BAR; PG8_MMA(1, 0, At, B0); PG8_MMA(1, 1, At, B1); PG8_BAR; PG8_SCHED;
	s_setprio 1
	s_waitcnt lgkmcnt(0)
	v_mfma_f32_16x16x32_bf16 v[124:127], v[154:157], v[186:189], v[124:127]
	v_mfma_f32_16x16x32_bf16 v[120:123], v[162:165], v[186:189], v[120:123]
	v_mfma_f32_16x16x32_bf16 v[108:111], v[154:157], v[194:197], v[108:111]
	v_mfma_f32_16x16x32_bf16 v[104:107], v[162:165], v[194:197], v[104:107]
	v_mfma_f32_16x16x32_bf16 v[92:95], v[154:157], v[208:211], v[92:95]
	v_mfma_f32_16x16x32_bf16 v[88:91], v[162:165], v[208:211], v[88:91]
	v_mfma_f32_16x16x32_bf16 v[76:79], v[154:157], v[216:219], v[76:79]
	v_mfma_f32_16x16x32_bf16 v[72:75], v[162:165], v[216:219], v[72:75]
	v_mfma_f32_16x16x32_bf16 v[124:127], v[158:161], v[190:193], v[124:127]
	v_mfma_f32_16x16x32_bf16 v[120:123], v[166:169], v[190:193], v[120:123]
	v_mfma_f32_16x16x32_bf16 v[108:111], v[158:161], v[198:201], v[108:111]
	v_mfma_f32_16x16x32_bf16 v[104:107], v[166:169], v[198:201], v[104:107]
	v_mfma_f32_16x16x32_bf16 v[92:95], v[158:161], v[212:215], v[92:95]
	v_mfma_f32_16x16x32_bf16 v[88:91], v[166:169], v[212:215], v[88:91]
	v_mfma_f32_16x16x32_bf16 v[76:79], v[158:161], v[220:223], v[76:79]
	v_mfma_f32_16x16x32_bf16 v[72:75], v[166:169], v[220:223], v[72:75]
	s_setprio 0
	s_setprio 1
	v_mfma_f32_16x16x32_bf16 v[116:119], v[170:173], v[186:189], v[116:119]
	v_mfma_f32_16x16x32_bf16 v[112:115], v[178:181], v[186:189], v[112:115]
	v_mfma_f32_16x16x32_bf16 v[100:103], v[170:173], v[194:197], v[100:103]
	v_mfma_f32_16x16x32_bf16 v[96:99], v[178:181], v[194:197], v[96:99]
	v_mfma_f32_16x16x32_bf16 v[84:87], v[170:173], v[208:211], v[84:87]
	v_mfma_f32_16x16x32_bf16 v[80:83], v[178:181], v[208:211], v[80:83]
	v_mfma_f32_16x16x32_bf16 v[68:71], v[170:173], v[216:219], v[68:71]
	v_mfma_f32_16x16x32_bf16 v[64:67], v[178:181], v[216:219], v[64:67]
	v_mfma_f32_16x16x32_bf16 v[116:119], v[174:177], v[190:193], v[116:119]
	v_mfma_f32_16x16x32_bf16 v[112:115], v[182:185], v[190:193], v[112:115]
	v_mfma_f32_16x16x32_bf16 v[100:103], v[174:177], v[198:201], v[100:103]
	v_mfma_f32_16x16x32_bf16 v[96:99], v[182:185], v[198:201], v[96:99]
	v_mfma_f32_16x16x32_bf16 v[84:87], v[174:177], v[212:215], v[84:87]
	v_mfma_f32_16x16x32_bf16 v[80:83], v[182:185], v[212:215], v[80:83]
	v_mfma_f32_16x16x32_bf16 v[68:71], v[174:177], v[220:223], v[68:71]
	v_mfma_f32_16x16x32_bf16 v[64:67], v[182:185], v[220:223], v[64:67]
	s_setprio 0
	s_barrier
	s_add_i32 s76, s76, s60
	v_lshl_add_u64 v[202:203], s[26:27], 0, v[138:139]
	s_mov_b32 m0, s76
	ds_read_b128 v[186:189], v153 offset:16384
	ds_read_b128 v[190:193], v153 offset:17408
	ds_read_b128 v[194:197], v153 offset:18432
	ds_read_b128 v[198:201], v153 offset:19456
	ds_read_b128 v[208:211], v153 offset:20480
	ds_read_b128 v[212:215], v153 offset:21504
	ds_read_b128 v[216:219], v153 offset:22528
	ds_read_b128 v[220:223], v153 offset:23552
	global_load_lds_dwordx4 v[202:203], off
	s_add_i32 m0, s76, 0x2000
	s_add_u32 s96, s26, 0x40000
	v_lshl_add_u64 v[224:225], s[26:27], 0, v[128:129]
	s_addc_u32 s97, s27, 0
	s_add_i32 s76, s77, s60
	global_load_lds_dwordx4 v[224:225], off
	v_lshl_add_u64 v[226:227], s[96:97], 0, v[138:139]
	s_mov_b32 m0, s76
	v_lshl_add_u64 v[228:229], s[42:43], 0, v[130:131]
	global_load_lds_dwordx4 v[226:227], off
	v_lshl_add_u64 v[226:227], s[96:97], 0, v[128:129]
	s_add_i32 m0, s76, 0x2000
	s_nop 0
	global_load_lds_dwordx4 v[226:227], off
	v_lshl_add_u64 v[226:227], s[42:43], 0, v[132:133]
	s_mov_b32 m0, s30
	s_nop 0
	global_load_lds_dwordx4 v[226:227], off
	s_mov_b32 m0, s61
	s_nop 0
	global_load_lds_dwordx4 v[228:229], off
	s_waitcnt vmcnt(8)
	s_waitcnt lgkmcnt(0)
	s_barrier
	s_setprio 1
	s_waitcnt lgkmcnt(0)
	v_mfma_f32_16x16x32_bf16 v[60:63], v[154:157], v[186:189], v[60:63]
	v_mfma_f32_16x16x32_bf16 v[56:59], v[162:165], v[186:189], v[56:59]
	v_mfma_f32_16x16x32_bf16 v[44:47], v[154:157], v[194:197], v[44:47]
	v_mfma_f32_16x16x32_bf16 v[40:43], v[162:165], v[194:197], v[40:43]
	v_mfma_f32_16x16x32_bf16 v[28:31], v[154:157], v[208:211], v[28:31]
	v_mfma_f32_16x16x32_bf16 v[24:27], v[162:165], v[208:211], v[24:27]
	v_mfma_f32_16x16x32_bf16 v[12:15], v[154:157], v[216:219], v[12:15]
	v_mfma_f32_16x16x32_bf16 v[8:11], v[162:165], v[216:219], v[8:11]
	v_mfma_f32_16x16x32_bf16 v[60:63], v[158:161], v[190:193], v[60:63]
	v_mfma_f32_16x16x32_bf16 v[56:59], v[166:169], v[190:193], v[56:59]
	v_mfma_f32_16x16x32_bf16 v[44:47], v[158:161], v[198:201], v[44:47]
	v_mfma_f32_16x16x32_bf16 v[40:43], v[166:169], v[198:201], v[40:43]
	v_mfma_f32_16x16x32_bf16 v[28:31], v[158:161], v[212:215], v[28:31]
	v_mfma_f32_16x16x32_bf16 v[24:27], v[166:169], v[212:215], v[24:27]
	v_mfma_f32_16x16x32_bf16 v[12:15], v[158:161], v[220:223], v[12:15]
	v_mfma_f32_16x16x32_bf16 v[8:11], v[166:169], v[220:223], v[8:11]
	s_setprio 0
	s_setprio 1
	v_mfma_f32_16x16x32_bf16 v[52:55], v[170:173], v[186:189], v[52:55]
	v_mfma_f32_16x16x32_bf16 v[48:51], v[178:181], v[186:189], v[48:51]
	v_mfma_f32_16x16x32_bf16 v[36:39], v[170:173], v[194:197], v[36:39]
	v_mfma_f32_16x16x32_bf16 v[32:35], v[178:181], v[194:197], v[32:35]
	v_mfma_f32_16x16x32_bf16 v[20:23], v[170:173], v[208:211], v[20:23]
	v_mfma_f32_16x16x32_bf16 v[16:19], v[178:181], v[208:211], v[16:19]
	v_mfma_f32_16x16x32_bf16 v[4:7], v[170:173], v[216:219], v[4:7]
	v_mfma_f32_16x16x32_bf16 v[0:3], v[178:181], v[216:219], v[0:3]
	v_mfma_f32_16x16x32_bf16 v[52:55], v[174:177], v[190:193], v[52:55]
	v_mfma_f32_16x16x32_bf16 v[48:51], v[182:185], v[190:193], v[48:51]
	v_mfma_f32_16x16x32_bf16 v[36:39], v[174:177], v[198:201], v[36:39]
	v_mfma_f32_16x16x32_bf16 v[32:35], v[182:185], v[198:201], v[32:35]
	v_mfma_f32_16x16x32_bf16 v[20:23], v[174:177], v[212:215], v[20:23]
	v_mfma_f32_16x16x32_bf16 v[16:19], v[182:185], v[212:215], v[16:19]
	v_mfma_f32_16x16x32_bf16 v[4:7], v[174:177], v[220:223], v[4:7]
	v_mfma_f32_16x16x32_bf16 v[0:3], v[182:185], v[220:223], v[0:3]
	s_setprio 0
	s_barrier
; #define PG8_STAGE(bufoff, gbase, voff) do { _Pragma("unroll") for (int _i = 0; _i < 2; ++_i) \
;         __builtin_amdgcn_global_load_lds((const unsigned*)((const char*)(gbase) + (voff)[_i]), (PG8_LAS unsigned*)(lds + (bufoff) + ldsw + _i * 8192), 16, 0, 0); } while (0)
; #define PG8_LDA(dst, b, h) do { _Pragma("unroll") for (int m = 0; m < 4; ++m) _Pragma("unroll") for (int k = 0; k < 2; ++k) dst[m][k] = *(const PG8_LAS bf16x8*)(lds + PG8_SA(b, h) + aoff + m * 2048 + k * 1024); } while (0)
; #define PG8_LDB(dst, b, h) do { _Pragma("unroll") for (int n = 0; n < 2; ++n) _Pragma("unroll") for (int k = 0; k < 2; ++k) dst[n][k] = *(const PG8_LAS bf16x8*)(lds + PG8_SB(b, h) + boff + n * 2048 + k * 1024); } while (0)
; #define PG8_MMA(ai, bj, At, Bt) do { __builtin_amdgcn_s_setprio(1); _Pragma("unroll") for (int m = 0; m < 4; ++m) _Pragma("unroll") for (int n = 0; n < 2; ++n) _Pragma("unroll") for (int k = 0; k < 2; ++k) \
;         acc[ai][bj][m][n] = __builtin_amdgcn_mfma_f32_16x16x32_bf16(Bt[n][k], At[m][k], acc[ai][bj][m][n], 0, 0, 0); __builtin_amdgcn_s_setprio(0); } while (0)
; #define PG8_WAIT_V(n) asm volatile("s_waitcnt vmcnt(" #n ")" ::: "memory")
; #define PG8_WAIT_L(n) asm volatile("s_waitcnt lgkmcnt(" #n ")" ::: "memory")
; #define PG8_BAR __builtin_amdgcn_s_barrier()
; #define PG8_SCHED __builtin_amdgcn_sched_barrier(0)
; template <class Epi, class Sched, bool ALIGN_EPI = false, bool SP2 = false>
; __device__ __forceinline__ void gemm_phase(PG8_LAS unsigned char* lds, const Gemm g, const Sched& S, const Epi& E) {
;     ...
;             PG8_LDB(B0, 1, 0); PG8_LDB(B1, 1, 1); PG8_SCHED; PG8_LDA(At, 1, 0); PG8_STAGE(PG8_SA(0, 1), a2 + hstep, voffA);
;             PG8_WAIT_V(8); PG8_WAIT_L(0); PG8_BAR; PG8_MMA(0, 0, At, B0); PG8_MMA(0, 1, At, B1); PG8_BAR; PG8_SCHED;
	s_add_i32 s76, 0, 0x18000
	s_add_i32 s77, 0, 0x1c000
	v_add_u32_e32 v166, s76, v151
	v_add_u32_e32 v182, s77, v151
	ds_read_b128 v[154:157], v166
	ds_read_b128 v[158:161], v166 offset:1024
	ds_read_b128 v[162:165], v166 offset:2048
	ds_read_b128 v[166:169], v166 offset:3072
	ds_read_b128 v[170:173], v182
	ds_read_b128 v[174:177], v182 offset:1024
	ds_read_b128 v[178:181], v182 offset:2048
	ds_read_b128 v[182:185], v182 offset:3072
	s_add_u32 s42, s42, 0x40000
	s_addc_u32 s43, s43, 0
	s_mov_b32 m0, s74
	v_lshl_add_u64 v[230:231], s[42:43], 0, v[132:133]
	ds_read_b128 v[186:189], v153 offset:32768
	ds_read_b128 v[190:193], v153 offset:33792
	ds_read_b128 v[194:197], v153 offset:34816
	ds_read_b128 v[198:201], v153 offset:35840
	ds_read_b128 v[208:211], v153 offset:36864
	ds_read_b128 v[212:215], v153 offset:37888
	ds_read_b128 v[216:219], v153 offset:38912
	ds_read_b128 v[220:223], v153 offset:39936
	global_load_lds_dwordx4 v[230:231], off
	v_lshl_add_u64 v[230:231], s[42:43], 0, v[130:131]
	s_mov_b32 m0, s75
	s_nop 0
	global_load_lds_dwordx4 v[230:231], off
	s_waitcnt vmcnt(8)
	s_waitcnt lgkmcnt(0)
	s_barrier
	s_setprio 1
	s_waitcnt lgkmcnt(0)
	v_mfma_f32_16x16x32_bf16 v[124:127], v[154:157], v[186:189], v[124:127]
	v_mfma_f32_16x16x32_bf16 v[120:123], v[162:165], v[186:189], v[120:123]
	v_mfma_f32_16x16x32_bf16 v[108:111], v[154:157], v[194:197], v[108:111]
	v_mfma_f32_16x16x32_bf16 v[104:107], v[162:165], v[194:197], v[104:107]
	v_mfma_f32_16x16x32_bf16 v[92:95], v[154:157], v[208:211], v[92:95]
	v_mfma_f32_16x16x32_bf16 v[88:91], v[162:165], v[208:211], v[88:91]
	v_mfma_f32_16x16x32_bf16 v[76:79], v[154:157], v[216:219], v[76:79]
	v_mfma_f32_16x16x32_bf16 v[72:75], v[162:165], v[216:219], v[72:75]
	v_mfma_f32_16x16x32_bf16 v[124:127], v[158:161], v[190:193], v[124:127]
	v_mfma_f32_16x16x32_bf16 v[120:123], v[166:169], v[190:193], v[120:123]
	v_mfma_f32_16x16x32_bf16 v[108:111], v[158:161], v[198:201], v[108:111]
	v_mfma_f32_16x16x32_bf16 v[104:107], v[166:169], v[198:201], v[104:107]
	v_mfma_f32_16x16x32_bf16 v[92:95], v[158:161], v[212:215], v[92:95]
	v_mfma_f32_16x16x32_bf16 v[88:91], v[166:169], v[212:215], v[88:91]
	v_mfma_f32_16x16x32_bf16 v[76:79], v[158:161], v[220:223], v[76:79]
	v_mfma_f32_16x16x32_bf16 v[72:75], v[166:169], v[220:223], v[72:75]
	s_setprio 0
	s_setprio 1
	v_mfma_f32_16x16x32_bf16 v[116:119], v[170:173], v[186:189], v[116:119]
	v_mfma_f32_16x16x32_bf16 v[112:115], v[178:181], v[186:189], v[112:115]
	v_mfma_f32_16x16x32_bf16 v[100:103], v[170:173], v[194:197], v[100:103]
	v_mfma_f32_16x16x32_bf16 v[96:99], v[178:181], v[194:197], v[96:99]
	v_mfma_f32_16x16x32_bf16 v[84:87], v[170:173], v[208:211], v[84:87]
	v_mfma_f32_16x16x32_bf16 v[80:83], v[178:181], v[208:211], v[80:83]
	v_mfma_f32_16x16x32_bf16 v[68:71], v[170:173], v[216:219], v[68:71]
	v_mfma_f32_16x16x32_bf16 v[64:67], v[178:181], v[216:219], v[64:67]
	v_mfma_f32_16x16x32_bf16 v[116:119], v[174:177], v[190:193], v[116:119]
	v_mfma_f32_16x16x32_bf16 v[112:115], v[182:185], v[190:193], v[112:115]
	v_mfma_f32_16x16x32_bf16 v[100:103], v[174:177], v[198:201], v[100:103]
	v_mfma_f32_16x16x32_bf16 v[96:99], v[182:185], v[198:201], v[96:99]
	v_mfma_f32_16x16x32_bf16 v[84:87], v[174:177], v[212:215], v[84:87]
	v_mfma_f32_16x16x32_bf16 v[80:83], v[182:185], v[212:215], v[80:83]
	v_mfma_f32_16x16x32_bf16 v[68:71], v[174:177], v[220:223], v[68:71]
	v_mfma_f32_16x16x32_bf16 v[64:67], v[182:185], v[220:223], v[64:67]
	s_setprio 0
	s_barrier
; #define PG8_STAGE(bufoff, gbase, voff) do { _Pragma("unroll") for (int _i = 0; _i < 2; ++_i) \
;         __builtin_amdgcn_global_load_lds((const unsigned*)((const char*)(gbase) + (voff)[_i]), (PG8_LAS unsigned*)(lds + (bufoff) + ldsw + _i * 8192), 16, 0, 0); } while (0)
; #define PG8_LDA(dst, b, h) do { _Pragma("unroll") for (int m = 0; m < 4; ++m) _Pragma("unroll") for (int k = 0; k < 2; ++k) dst[m][k] = *(const PG8_LAS bf16x8*)(lds + PG8_SA(b, h) + aoff + m * 2048 + k * 1024); } while (0)
; #define PG8_MMA(ai, bj, At, Bt) do { __builtin_amdgcn_s_setprio(1); _Pragma("unroll") for (int m = 0; m < 4; ++m) _Pragma("unroll") for (int n = 0; n < 2; ++n) _Pragma("unroll") for (int k = 0; k < 2; ++k) \
;         acc[ai][bj][m][n] = __builtin_amdgcn_mfma_f32_16x16x32_bf16(Bt[n][k], At[m][k], acc[ai][bj][m][n], 0, 0, 0); __builtin_amdgcn_s_setprio(0); } while (0)
; #define PG8_WAIT_V(n) asm volatile("s_waitcnt vmcnt(" #n ")" ::: "memory")
; #define PG8_WAIT_L(n) asm volatile("s_waitcnt lgkmcnt(" #n ")" ::: "memory")
; #define PG8_BAR __builtin_amdgcn_s_barrier()
; #define PG8_SCHED __builtin_amdgcn_sched_barrier(0)
; template <class Epi, class Sched, bool ALIGN_EPI = false, bool SP2 = false>
; __device__ __forceinline__ void gemm_phase(PG8_LAS unsigned char* lds, const Gemm g, const Sched& S, const Epi& E) {
;     ...
;         for (int t = 0; t < nt; t += 2) {
;             const bool last = (t == nt - 2);
;             const char* a1 = cA + (size_t)(t + 1) * kstep;
;             const char* a2 = last ? nA : cA + (size_t)(t + 2) * kstep; const char* b2 = last ? nB : cB + (size_t)(t + 2) * kstep;
;     ...
;             PG8_LDA(At, 1, 1); PG8_STAGE(PG8_SB(1, 0), b3, voffB); PG8_STAGE(PG8_SB(1, 1), b3 + hstep, voffB); PG8_STAGE(PG8_SA(1, 0), a3, voffA);
;             PG8_WAIT_V(8); PG8_WAIT_L(0); PG8_BAR; PG8_MMA(1, 0, At, B0); PG8_MMA(1, 1, At, B1); PG8_BAR; PG8_SCHED;
	s_add_i32 s42, s76, s60
	v_lshl_add_u64 v[202:203], v[202:203], 0, s[34:35]
	s_mov_b32 m0, s42
	ds_read_b128 v[186:189], v153 offset:49152
	ds_read_b128 v[190:193], v153 offset:50176
	ds_read_b128 v[194:197], v153 offset:51200
	ds_read_b128 v[198:201], v153 offset:52224
	ds_read_b128 v[208:211], v153 offset:53248
	ds_read_b128 v[212:215], v153 offset:54272
	ds_read_b128 v[216:219], v153 offset:55296
	ds_read_b128 v[220:223], v153 offset:56320
	global_load_lds_dwordx4 v[202:203], off
	s_add_i32 m0, s42, 0x2000
	s_add_u32 s26, s26, 0x40080
	v_lshl_add_u64 v[202:203], v[224:225], 0, s[34:35]
	s_addc_u32 s27, s27, 0
	s_add_i32 s42, s77, s60
	global_load_lds_dwordx4 v[202:203], off
	v_lshl_add_u64 v[202:203], s[26:27], 0, v[138:139]
	s_mov_b32 m0, s42
	s_nop 0
	global_load_lds_dwordx4 v[202:203], off
	v_lshl_add_u64 v[202:203], s[26:27], 0, v[128:129]
	s_add_i32 m0, s42, 0x2000
	s_nop 0
	global_load_lds_dwordx4 v[202:203], off
	v_lshl_add_u64 v[202:203], v[226:227], 0, s[34:35]
	s_mov_b32 m0, s88
	s_nop 0
	global_load_lds_dwordx4 v[202:203], off
	v_lshl_add_u64 v[202:203], v[228:229], 0, s[34:35]
	s_mov_b32 m0, s89
	s_nop 0
	global_load_lds_dwordx4 v[202:203], off
	s_waitcnt vmcnt(8)
	s_waitcnt lgkmcnt(0)
	s_barrier
	s_setprio 1
	s_waitcnt lgkmcnt(0)
	v_mfma_f32_16x16x32_bf16 v[60:63], v[154:157], v[186:189], v[60:63]
	v_mfma_f32_16x16x32_bf16 v[56:59], v[162:165], v[186:189], v[56:59]
	v_mfma_f32_16x16x32_bf16 v[44:47], v[154:157], v[194:197], v[44:47]
	v_mfma_f32_16x16x32_bf16 v[40:43], v[162:165], v[194:197], v[40:43]
	v_mfma_f32_16x16x32_bf16 v[28:31], v[154:157], v[208:211], v[28:31]
	v_mfma_f32_16x16x32_bf16 v[24:27], v[162:165], v[208:211], v[24:27]
	v_mfma_f32_16x16x32_bf16 v[12:15], v[154:157], v[216:219], v[12:15]
	v_mfma_f32_16x16x32_bf16 v[8:11], v[162:165], v[216:219], v[8:11]
	v_mfma_f32_16x16x32_bf16 v[60:63], v[158:161], v[190:193], v[60:63]
	v_mfma_f32_16x16x32_bf16 v[56:59], v[166:169], v[190:193], v[56:59]
	v_mfma_f32_16x16x32_bf16 v[44:47], v[158:161], v[198:201], v[44:47]
	v_mfma_f32_16x16x32_bf16 v[40:43], v[166:169], v[198:201], v[40:43]
	v_mfma_f32_16x16x32_bf16 v[28:31], v[158:161], v[212:215], v[28:31]
	v_mfma_f32_16x16x32_bf16 v[24:27], v[166:169], v[212:215], v[24:27]
	v_mfma_f32_16x16x32_bf16 v[12:15], v[158:161], v[220:223], v[12:15]
	v_mfma_f32_16x16x32_bf16 v[8:11], v[166:169], v[220:223], v[8:11]
	s_setprio 0
	s_setprio 1
	v_mfma_f32_16x16x32_bf16 v[52:55], v[170:173], v[186:189], v[52:55]
	s_add_i32 s94, s94, 2
	s_add_u32 s24, s24, 0x100
	s_addc_u32 s25, s25, 0
	v_mfma_f32_16x16x32_bf16 v[48:51], v[178:181], v[186:189], v[48:51]
	s_add_u32 s36, s36, 0x100
	s_addc_u32 s37, s37, 0
	s_add_u32 s26, s24, 0xfffc0080
	v_mfma_f32_16x16x32_bf16 v[36:39], v[170:173], v[194:197], v[36:39]
	s_addc_u32 s27, s25, -1
	s_add_i32 s76, 0, 0x10000
	s_cmp_eq_u32 s94, 12
	v_mfma_f32_16x16x32_bf16 v[32:35], v[178:181], v[194:197], v[32:35]
	s_cselect_b32 s43, s47, s27
	s_cselect_b32 s42, vcc_lo, s26
	s_cselect_b32 s27, s29, s37
	v_mfma_f32_16x16x32_bf16 v[20:23], v[170:173], v[208:211], v[20:23]
	s_cselect_b32 s26, vcc_hi, s36
	s_add_i32 s77, 0, 0x14000
	s_cmp_gt_u32 s94, 13
	v_mfma_f32_16x16x32_bf16 v[16:19], v[178:181], v[208:211], v[16:19]
	v_mfma_f32_16x16x32_bf16 v[4:7], v[170:173], v[216:219], v[4:7]
	v_mfma_f32_16x16x32_bf16 v[0:3], v[178:181], v[216:219], v[0:3]
	v_mfma_f32_16x16x32_bf16 v[52:55], v[174:177], v[190:193], v[52:55]
	v_mfma_f32_16x16x32_bf16 v[48:51], v[182:185], v[190:193], v[48:51]
	v_mfma_f32_16x16x32_bf16 v[36:39], v[174:177], v[198:201], v[36:39]
	v_mfma_f32_16x16x32_bf16 v[32:35], v[182:185], v[198:201], v[32:35]
	v_mfma_f32_16x16x32_bf16 v[20:23], v[174:177], v[212:215], v[20:23]
	v_mfma_f32_16x16x32_bf16 v[16:19], v[182:185], v[212:215], v[16:19]
	v_mfma_f32_16x16x32_bf16 v[4:7], v[174:177], v[220:223], v[4:7]
	v_mfma_f32_16x16x32_bf16 v[0:3], v[182:185], v[220:223], v[0:3]
	s_setprio 0
	s_barrier
	s_cbranch_scc0 .LBB0_1059
	s_and_b64 vcc, exec, s[22:23]
	s_cbranch_vccz .LBB0_1062
	s_barrier

; template <class Epi, class Sched, bool ALIGN_EPI = false, bool SP2 = false>
; __device__ __forceinline__ void gemm_phase(PG8_LAS unsigned char* lds, const Gemm g, const Sched& S, const Epi& E) {
;     ...
;         const bool has_next = S.next(ui + 1, nxt);
;         const char* nA = has_next ? (const char*)g.A + (size_t)nxt.pm * tstep : cA; const char* nB = has_next ? (const char*)g.Bt + (size_t)nxt.pn * tstep : cB;
;         for (int t = 0; t < nt; t += 2) {
;             const bool last = (t == nt - 2);
;             const char* a1 = cA + (size_t)(t + 1) * kstep;
;             const char* a2 = last ? nA : cA + (size_t)(t + 2) * kstep; const char* b2 = last ? nB : cB + (size_t)(t + 2) * kstep;
;     ...
; #pragma unroll
;         for (int a = 0; a < 2; ++a)
; #pragma unroll
;             for (int b = 0; b < 2; ++b)
; #pragma unroll
;                 for (int m = 0; m < 4; ++m)
; #pragma unroll
;                     for (int n = 0; n < 2; ++n) acc[a][b][m][n] = (f32x4){0.f, 0.f, 0.f, 0.f};
;         cur = nxt; cA = nA; cB = nB; ++ui;
.LBB0_1151:
	s_ashr_i32 s75, s74, 31
	s_lshl_b64 s[22:23], s[74:75], 19
	s_add_u32 s28, s72, s22
	s_addc_u32 s29, s73, s23
	s_and_b64 s[22:23], s[38:39], exec
	s_cselect_b32 s75, s29, s25
	s_cselect_b32 s89, s28, s24
	s_ashr_i32 s61, s60, 31
	s_lshl_b64 s[22:23], s[60:61], 19
	s_add_u32 s22, s46, s22
	s_addc_u32 s23, s47, s23
	s_and_b64 s[36:37], s[38:39], exec
	s_cselect_b32 s61, s23, s27
	s_cselect_b32 s92, s22, s26
	s_add_u32 s24, s24, 0x40080
	s_addc_u32 s25, s25, 0
	s_add_u32 s36, s26, 0x100
	v_mov_b32_e32 v0, 0
	s_addc_u32 s37, s27, 0
	s_mov_b32 s93, -2
	v_mov_b32_e32 v1, v0
	v_mov_b32_e32 v2, v0
	v_mov_b32_e32 v3, v0
	v_mov_b32_e32 v4, v0
	v_mov_b32_e32 v5, v0
	v_mov_b32_e32 v6, v0
	v_mov_b32_e32 v7, v0
	v_mov_b32_e32 v16, v0
	v_mov_b32_e32 v17, v0
	v_mov_b32_e32 v18, v0
	v_mov_b32_e32 v19, v0
	v_mov_b32_e32 v20, v0
	v_mov_b32_e32 v21, v0
	v_mov_b32_e32 v22, v0
	v_mov_b32_e32 v23, v0
	s_waitcnt vmcnt(0)
	v_mov_b32_e32 v32, v0
	v_mov_b32_e32 v33, v0
	v_mov_b32_e32 v34, v0
	v_mov_b32_e32 v35, v0
	v_mov_b32_e32 v36, v0
	v_mov_b32_e32 v37, v0
	v_mov_b32_e32 v38, v0
	v_mov_b32_e32 v39, v0
	v_mov_b32_e32 v48, v0
	v_mov_b32_e32 v49, v0
	v_mov_b32_e32 v50, v0
	v_mov_b32_e32 v51, v0
	v_mov_b32_e32 v52, v0
	v_mov_b32_e32 v53, v0
	v_mov_b32_e32 v54, v0
	v_mov_b32_e32 v55, v0
	v_mov_b32_e32 v8, v0
	v_mov_b32_e32 v9, v0
	v_mov_b32_e32 v10, v0
	v_mov_b32_e32 v11, v0
	v_mov_b32_e32 v12, v0
	v_mov_b32_e32 v13, v0
	v_mov_b32_e32 v14, v0
	v_mov_b32_e32 v15, v0
	v_mov_b32_e32 v24, v0
	v_mov_b32_e32 v25, v0
	v_mov_b32_e32 v26, v0
	v_mov_b32_e32 v27, v0
	v_mov_b32_e32 v28, v0
	v_mov_b32_e32 v29, v0
	v_mov_b32_e32 v30, v0
	v_mov_b32_e32 v31, v0
	v_mov_b32_e32 v40, v0
	v_mov_b32_e32 v41, v0
	v_mov_b32_e32 v42, v0
	v_mov_b32_e32 v43, v0
	v_mov_b32_e32 v44, v0
	v_mov_b32_e32 v45, v0
	v_mov_b32_e32 v46, v0
	v_mov_b32_e32 v47, v0
	v_mov_b32_e32 v56, v0
	v_mov_b32_e32 v57, v0
	v_mov_b32_e32 v58, v0
	v_mov_b32_e32 v59, v0
	v_mov_b32_e32 v60, v0
	v_mov_b32_e32 v61, v0
	v_mov_b32_e32 v62, v0
	v_mov_b32_e32 v63, v0
	v_mov_b32_e32 v64, v0
	v_mov_b32_e32 v65, v0
	v_mov_b32_e32 v66, v0
	v_mov_b32_e32 v67, v0
	v_mov_b32_e32 v68, v0
	v_mov_b32_e32 v69, v0
	v_mov_b32_e32 v70, v0
	v_mov_b32_e32 v71, v0
	v_mov_b32_e32 v80, v0
	v_mov_b32_e32 v81, v0
	v_mov_b32_e32 v82, v0
	v_mov_b32_e32 v83, v0
	v_mov_b32_e32 v84, v0
	v_mov_b32_e32 v85, v0
	v_mov_b32_e32 v86, v0
	v_mov_b32_e32 v87, v0
	v_mov_b32_e32 v96, v0
	v_mov_b32_e32 v97, v0
	v_mov_b32_e32 v98, v0
	v_mov_b32_e32 v99, v0
	v_mov_b32_e32 v100, v0
	v_mov_b32_e32 v101, v0
	v_mov_b32_e32 v102, v0
	v_mov_b32_e32 v103, v0
	v_mov_b32_e32 v112, v0
	v_mov_b32_e32 v113, v0
	v_mov_b32_e32 v114, v0
	v_mov_b32_e32 v115, v0
	v_mov_b32_e32 v116, v0
	v_mov_b32_e32 v117, v0
	v_mov_b32_e32 v118, v0
	v_mov_b32_e32 v119, v0
	v_mov_b32_e32 v72, v0
	v_mov_b32_e32 v73, v0
	v_mov_b32_e32 v74, v0
	v_mov_b32_e32 v75, v0
	v_mov_b32_e32 v76, v0
	v_mov_b32_e32 v77, v0
	v_mov_b32_e32 v78, v0
	v_mov_b32_e32 v79, v0
	v_mov_b32_e32 v88, v0
	v_mov_b32_e32 v89, v0
	v_mov_b32_e32 v90, v0
	v_mov_b32_e32 v91, v0
	v_mov_b32_e32 v92, v0
	v_mov_b32_e32 v93, v0
	v_mov_b32_e32 v94, v0
	v_mov_b32_e32 v95, v0
	v_mov_b32_e32 v104, v0
	v_mov_b32_e32 v105, v0
	v_mov_b32_e32 v106, v0
	v_mov_b32_e32 v107, v0
	v_mov_b32_e32 v108, v0
	v_mov_b32_e32 v109, v0
	v_mov_b32_e32 v110, v0
	v_mov_b32_e32 v111, v0
	v_mov_b32_e32 v120, v0
	v_mov_b32_e32 v121, v0
	v_mov_b32_e32 v122, v0
	v_mov_b32_e32 v123, v0
	v_mov_b32_e32 v124, v0
	v_mov_b32_e32 v125, v0
	v_mov_b32_e32 v126, v0
	v_mov_b32_e32 v127, v0
	s_add_u32 s26, s24, 0xfffc0080
	s_addc_u32 s27, s25, -1
	s_add_i32 s76, 0, 0x10000
	s_cmp_eq_u32 s93, 12
	s_cselect_b32 s43, s75, s27
	s_cselect_b32 s42, s89, s26
	s_cselect_b32 s27, s61, s37
	s_cselect_b32 s26, s92, s36
	s_add_i32 s77, 0, 0x14000
.LBB0_1152:
	v_add_u32_e32 v166, s76, v155
	v_add_u32_e32 v182, s77, v155
	ds_read_b128 v[150:153], v166
	ds_read_b128 v[158:161], v166 offset:1024
	ds_read_b128 v[162:165], v166 offset:2048
	ds_read_b128 v[166:169], v166 offset:3072
	ds_read_b128 v[170:173], v182
	ds_read_b128 v[174:177], v182 offset:1024
	ds_read_b128 v[178:181], v182 offset:2048
	ds_read_b128 v[182:185], v182 offset:3072
	v_lshl_add_u64 v[202:203], s[24:25], 0, v[134:135]
	s_add_i32 m0, s49, 0xc000
	ds_read_b128 v[186:189], v157
	ds_read_b128 v[190:193], v157 offset:1024
	ds_read_b128 v[194:197], v157 offset:2048
	ds_read_b128 v[198:201], v157 offset:3072
	ds_read_b128 v[208:211], v157 offset:4096
	ds_read_b128 v[212:215], v157 offset:5120
	ds_read_b128 v[216:219], v157 offset:6144
	ds_read_b128 v[220:223], v157 offset:7168
	global_load_lds_dwordx4 v[202:203], off
	v_lshl_add_u64 v[202:203], s[24:25], 0, v[148:149]
	s_add_i32 m0, s49, 0xe000
	s_nop 0
	global_load_lds_dwordx4 v[202:203], off
	s_waitcnt vmcnt(8)
	s_waitcnt lgkmcnt(0)
	s_barrier
; #define PG8_STAGE(bufoff, gbase, voff) do { _Pragma("unroll") for (int _i = 0; _i < 2; ++_i) \
;         __builtin_amdgcn_global_load_lds((const unsigned*)((const char*)(gbase) + (voff)[_i]), (PG8_LAS unsigned*)(lds + (bufoff) + ldsw + _i * 8192), 16, 0, 0); } while (0)
; #define PG8_LDA(dst, b, h) do { _Pragma("unroll") for (int m = 0; m < 4; ++m) _Pragma("unroll") for (int k = 0; k < 2; ++k) dst[m][k] = *(const PG8_LAS bf16x8*)(lds + PG8_SA(b, h) + aoff + m * 2048 + k * 1024); } while (0)
; #define PG8_LDB(dst, b, h) do { _Pragma("unroll") for (int n = 0; n < 2; ++n) _Pragma("unroll") for (int k = 0; k < 2; ++k) dst[n][k] = *(const PG8_LAS bf16x8*)(lds + PG8_SB(b, h) + boff + n * 2048 + k * 1024); } while (0)
; #define PG8_MMA(ai, bj, At, Bt) do { __builtin_amdgcn_s_setprio(1); _Pragma("unroll") for (int m = 0; m < 4; ++m) _Pragma("unroll") for (int n = 0; n < 2; ++n) _Pragma("unroll") for (int k = 0; k < 2; ++k) \
;         acc[ai][bj][m][n] = __builtin_amdgcn_mfma_f32_16x16x32_bf16(Bt[n][k], At[m][k], acc[ai][bj][m][n], 0, 0, 0); __builtin_amdgcn_s_setprio(0); } while (0)
; #define PG8_WAIT_V(n) asm volatile("s_waitcnt vmcnt(" #n ")" ::: "memory")
; #define PG8_WAIT_L(n) asm volatile("s_waitcnt lgkmcnt(" #n ")" ::: "memory")
; #define PG8_BAR __builtin_amdgcn_s_barrier()
; #define PG8_SCHED __builtin_amdgcn_sched_barrier(0)
; template <class Epi, class Sched, bool ALIGN_EPI = false, bool SP2 = false>
; __device__ __forceinline__ void gemm_phase(PG8_LAS unsigned char* lds, const Gemm g, const Sched& S, const Epi& E) {
;     ...
;             PG8_LDB(B0, 0, 0); PG8_LDB(B1, 0, 1); PG8_SCHED; PG8_LDA(At, 0, 0); PG8_STAGE(PG8_SA(1, 1), a1 + hstep, voffA);
;             PG8_WAIT_V(8); PG8_WAIT_L(0); PG8_BAR; PG8_MMA(0, 0, At, B0); PG8_MMA(0, 1, At, B1); PG8_BAR; PG8_SCHED;
;             PG8_LDA(At, 0, 1); PG8_STAGE(PG8_SB(0, 0), b2, voffB); PG8_STAGE(PG8_SB(0, 1), b2 + hstep, voffB); PG8_STAGE(PG8_SA(0, 0), a2, voffA);
;             PG8_WAIT_V(8); PG8_WAIT_L(0); PG8_BAR; PG8_MMA(1, 0, At, B0); PG8_MMA(1, 1, At, B1); PG8_BAR; PG8_SCHED;
	s_setprio 1
	s_waitcnt lgkmcnt(0)
	v_mfma_f32_16x16x32_bf16 v[124:127], v[150:153], v[186:189], v[124:127]
	v_mfma_f32_16x16x32_bf16 v[120:123], v[162:165], v[186:189], v[120:123]
	v_mfma_f32_16x16x32_bf16 v[108:111], v[150:153], v[194:197], v[108:111]
	v_mfma_f32_16x16x32_bf16 v[104:107], v[162:165], v[194:197], v[104:107]
	v_mfma_f32_16x16x32_bf16 v[92:95], v[150:153], v[208:211], v[92:95]
	v_mfma_f32_16x16x32_bf16 v[88:91], v[162:165], v[208:211], v[88:91]
	v_mfma_f32_16x16x32_bf16 v[76:79], v[150:153], v[216:219], v[76:79]
	v_mfma_f32_16x16x32_bf16 v[72:75], v[162:165], v[216:219], v[72:75]
	v_mfma_f32_16x16x32_bf16 v[124:127], v[158:161], v[190:193], v[124:127]
	v_mfma_f32_16x16x32_bf16 v[120:123], v[166:169], v[190:193], v[120:123]
	v_mfma_f32_16x16x32_bf16 v[108:111], v[158:161], v[198:201], v[108:111]
	v_mfma_f32_16x16x32_bf16 v[104:107], v[166:169], v[198:201], v[104:107]
	v_mfma_f32_16x16x32_bf16 v[92:95], v[158:161], v[212:215], v[92:95]
	v_mfma_f32_16x16x32_bf16 v[88:91], v[166:169], v[212:215], v[88:91]
	v_mfma_f32_16x16x32_bf16 v[76:79], v[158:161], v[220:223], v[76:79]
	v_mfma_f32_16x16x32_bf16 v[72:75], v[166:169], v[220:223], v[72:75]
	s_setprio 0
	s_setprio 1
	v_mfma_f32_16x16x32_bf16 v[116:119], v[170:173], v[186:189], v[116:119]
	v_mfma_f32_16x16x32_bf16 v[112:115], v[178:181], v[186:189], v[112:115]
	v_mfma_f32_16x16x32_bf16 v[100:103], v[170:173], v[194:197], v[100:103]
	v_mfma_f32_16x16x32_bf16 v[96:99], v[178:181], v[194:197], v[96:99]
	v_mfma_f32_16x16x32_bf16 v[84:87], v[170:173], v[208:211], v[84:87]
	v_mfma_f32_16x16x32_bf16 v[80:83], v[178:181], v[208:211], v[80:83]
	v_mfma_f32_16x16x32_bf16 v[68:71], v[170:173], v[216:219], v[68:71]
	v_mfma_f32_16x16x32_bf16 v[64:67], v[178:181], v[216:219], v[64:67]
	v_mfma_f32_16x16x32_bf16 v[116:119], v[174:177], v[190:193], v[116:119]
	v_mfma_f32_16x16x32_bf16 v[112:115], v[182:185], v[190:193], v[112:115]
	v_mfma_f32_16x16x32_bf16 v[100:103], v[174:177], v[198:201], v[100:103]
	v_mfma_f32_16x16x32_bf16 v[96:99], v[182:185], v[198:201], v[96:99]
	v_mfma_f32_16x16x32_bf16 v[84:87], v[174:177], v[212:215], v[84:87]
	v_mfma_f32_16x16x32_bf16 v[80:83], v[182:185], v[212:215], v[80:83]
	v_mfma_f32_16x16x32_bf16 v[68:71], v[174:177], v[220:223], v[68:71]
	v_mfma_f32_16x16x32_bf16 v[64:67], v[182:185], v[220:223], v[64:67]
	s_setprio 0
	s_barrier
	s_add_i32 s76, s76, s48
	v_lshl_add_u64 v[202:203], s[26:27], 0, v[138:139]
	s_mov_b32 m0, s76
	ds_read_b128 v[186:189], v157 offset:16384
	ds_read_b128 v[190:193], v157 offset:17408
	ds_read_b128 v[194:197], v157 offset:18432
	ds_read_b128 v[198:201], v157 offset:19456
	ds_read_b128 v[208:211], v157 offset:20480
	ds_read_b128 v[212:215], v157 offset:21504
	ds_read_b128 v[216:219], v157 offset:22528
	ds_read_b128 v[220:223], v157 offset:23552
	global_load_lds_dwordx4 v[202:203], off
	s_add_i32 m0, s76, 0x2000
	s_add_u32 s94, s26, 0x40000
	v_lshl_add_u64 v[224:225], s[26:27], 0, v[128:129]
	s_addc_u32 s95, s27, 0
	s_add_i32 s76, s77, s48
	global_load_lds_dwordx4 v[224:225], off
	v_lshl_add_u64 v[226:227], s[94:95], 0, v[138:139]
	s_mov_b32 m0, s76
	v_lshl_add_u64 v[228:229], s[42:43], 0, v[130:131]
	global_load_lds_dwordx4 v[226:227], off
	v_lshl_add_u64 v[226:227], s[94:95], 0, v[128:129]
	s_add_i32 m0, s76, 0x2000
	s_nop 0
	global_load_lds_dwordx4 v[226:227], off
	v_lshl_add_u64 v[226:227], s[42:43], 0, v[132:133]
	s_mov_b32 m0, s49
	s_nop 0
	global_load_lds_dwordx4 v[226:227], off
	s_mov_b32 m0, s52
	s_nop 0
	global_load_lds_dwordx4 v[228:229], off
	s_waitcnt vmcnt(8)
	s_waitcnt lgkmcnt(0)
	s_barrier
	s_setprio 1
	s_waitcnt lgkmcnt(0)
	v_mfma_f32_16x16x32_bf16 v[60:63], v[150:153], v[186:189], v[60:63]
	v_mfma_f32_16x16x32_bf16 v[56:59], v[162:165], v[186:189], v[56:59]
	v_mfma_f32_16x16x32_bf16 v[44:47], v[150:153], v[194:197], v[44:47]
	v_mfma_f32_16x16x32_bf16 v[40:43], v[162:165], v[194:197], v[40:43]
	v_mfma_f32_16x16x32_bf16 v[28:31], v[150:153], v[208:211], v[28:31]
	v_mfma_f32_16x16x32_bf16 v[24:27], v[162:165], v[208:211], v[24:27]
	v_mfma_f32_16x16x32_bf16 v[12:15], v[150:153], v[216:219], v[12:15]
	v_mfma_f32_16x16x32_bf16 v[8:11], v[162:165], v[216:219], v[8:11]
	v_mfma_f32_16x16x32_bf16 v[60:63], v[158:161], v[190:193], v[60:63]
	v_mfma_f32_16x16x32_bf16 v[56:59], v[166:169], v[190:193], v[56:59]
	v_mfma_f32_16x16x32_bf16 v[44:47], v[158:161], v[198:201], v[44:47]
	v_mfma_f32_16x16x32_bf16 v[40:43], v[166:169], v[198:201], v[40:43]
	v_mfma_f32_16x16x32_bf16 v[28:31], v[158:161], v[212:215], v[28:31]
	v_mfma_f32_16x16x32_bf16 v[24:27], v[166:169], v[212:215], v[24:27]
	v_mfma_f32_16x16x32_bf16 v[12:15], v[158:161], v[220:223], v[12:15]
	v_mfma_f32_16x16x32_bf16 v[8:11], v[166:169], v[220:223], v[8:11]
	s_setprio 0
	s_setprio 1
	v_mfma_f32_16x16x32_bf16 v[52:55], v[170:173], v[186:189], v[52:55]
	v_mfma_f32_16x16x32_bf16 v[48:51], v[178:181], v[186:189], v[48:51]
	v_mfma_f32_16x16x32_bf16 v[36:39], v[170:173], v[194:197], v[36:39]
	v_mfma_f32_16x16x32_bf16 v[32:35], v[178:181], v[194:197], v[32:35]
	v_mfma_f32_16x16x32_bf16 v[20:23], v[170:173], v[208:211], v[20:23]
	v_mfma_f32_16x16x32_bf16 v[16:19], v[178:181], v[208:211], v[16:19]
	v_mfma_f32_16x16x32_bf16 v[4:7], v[170:173], v[216:219], v[4:7]
	v_mfma_f32_16x16x32_bf16 v[0:3], v[178:181], v[216:219], v[0:3]
	v_mfma_f32_16x16x32_bf16 v[52:55], v[174:177], v[190:193], v[52:55]
	v_mfma_f32_16x16x32_bf16 v[48:51], v[182:185], v[190:193], v[48:51]
	v_mfma_f32_16x16x32_bf16 v[36:39], v[174:177], v[198:201], v[36:39]
	v_mfma_f32_16x16x32_bf16 v[32:35], v[182:185], v[198:201], v[32:35]
	v_mfma_f32_16x16x32_bf16 v[20:23], v[174:177], v[212:215], v[20:23]
	v_mfma_f32_16x16x32_bf16 v[16:19], v[182:185], v[212:215], v[16:19]
	v_mfma_f32_16x16x32_bf16 v[4:7], v[174:177], v[220:223], v[4:7]
	v_mfma_f32_16x16x32_bf16 v[0:3], v[182:185], v[220:223], v[0:3]
	s_setprio 0
	s_barrier
; #define PG8_STAGE(bufoff, gbase, voff) do { _Pragma("unroll") for (int _i = 0; _i < 2; ++_i) \
;         __builtin_amdgcn_global_load_lds((const unsigned*)((const char*)(gbase) + (voff)[_i]), (PG8_LAS unsigned*)(lds + (bufoff) + ldsw + _i * 8192), 16, 0, 0); } while (0)
; #define PG8_LDA(dst, b, h) do { _Pragma("unroll") for (int m = 0; m < 4; ++m) _Pragma("unroll") for (int k = 0; k < 2; ++k) dst[m][k] = *(const PG8_LAS bf16x8*)(lds + PG8_SA(b, h) + aoff + m * 2048 + k * 1024); } while (0)
; #define PG8_LDB(dst, b, h) do { _Pragma("unroll") for (int n = 0; n < 2; ++n) _Pragma("unroll") for (int k = 0; k < 2; ++k) dst[n][k] = *(const PG8_LAS bf16x8*)(lds + PG8_SB(b, h) + boff + n * 2048 + k * 1024); } while (0)
; #define PG8_MMA(ai, bj, At, Bt) do { __builtin_amdgcn_s_setprio(1); _Pragma("unroll") for (int m = 0; m < 4; ++m) _Pragma("unroll") for (int n = 0; n < 2; ++n) _Pragma("unroll") for (int k = 0; k < 2; ++k) \
;         acc[ai][bj][m][n] = __builtin_amdgcn_mfma_f32_16x16x32_bf16(Bt[n][k], At[m][k], acc[ai][bj][m][n], 0, 0, 0); __builtin_amdgcn_s_setprio(0); } while (0)
; #define PG8_WAIT_V(n) asm volatile("s_waitcnt vmcnt(" #n ")" ::: "memory")
; #define PG8_WAIT_L(n) asm volatile("s_waitcnt lgkmcnt(" #n ")" ::: "memory")
; #define PG8_BAR __builtin_amdgcn_s_barrier()
; #define PG8_SCHED __builtin_amdgcn_sched_barrier(0)
; template <class Epi, class Sched, bool ALIGN_EPI = false, bool SP2 = false>
; __device__ __forceinline__ void gemm_phase(PG8_LAS unsigned char* lds, const Gemm g, const Sched& S, const Epi& E) {
;     ...
;             PG8_LDB(B0, 1, 0); PG8_LDB(B1, 1, 1); PG8_SCHED; PG8_LDA(At, 1, 0); PG8_STAGE(PG8_SA(0, 1), a2 + hstep, voffA);
;             PG8_WAIT_V(8); PG8_WAIT_L(0); PG8_BAR; PG8_MMA(0, 0, At, B0); PG8_MMA(0, 1, At, B1); PG8_BAR; PG8_SCHED;
	s_add_i32 s76, 0, 0x18000
	s_add_i32 s77, 0, 0x1c000
	v_add_u32_e32 v166, s76, v155
	v_add_u32_e32 v182, s77, v155
	ds_read_b128 v[150:153], v166
	ds_read_b128 v[158:161], v166 offset:1024
	ds_read_b128 v[162:165], v166 offset:2048
	ds_read_b128 v[166:169], v166 offset:3072
	ds_read_b128 v[170:173], v182
	ds_read_b128 v[174:177], v182 offset:1024
	ds_read_b128 v[178:181], v182 offset:2048
	ds_read_b128 v[182:185], v182 offset:3072
	s_add_u32 s42, s42, 0x40000
	s_addc_u32 s43, s43, 0
	s_mov_b32 m0, s53
	v_lshl_add_u64 v[230:231], s[42:43], 0, v[132:133]
	ds_read_b128 v[186:189], v157 offset:32768
	ds_read_b128 v[190:193], v157 offset:33792
	ds_read_b128 v[194:197], v157 offset:34816
	ds_read_b128 v[198:201], v157 offset:35840
	ds_read_b128 v[208:211], v157 offset:36864
	ds_read_b128 v[212:215], v157 offset:37888
	ds_read_b128 v[216:219], v157 offset:38912
	ds_read_b128 v[220:223], v157 offset:39936
	global_load_lds_dwordx4 v[230:231], off
	v_lshl_add_u64 v[230:231], s[42:43], 0, v[130:131]
	s_mov_b32 m0, s54
	s_nop 0
	global_load_lds_dwordx4 v[230:231], off
	s_waitcnt vmcnt(8)
	s_waitcnt lgkmcnt(0)
	s_barrier
	s_setprio 1
	s_waitcnt lgkmcnt(0)
	v_mfma_f32_16x16x32_bf16 v[124:127], v[150:153], v[186:189], v[124:127]
	v_mfma_f32_16x16x32_bf16 v[120:123], v[162:165], v[186:189], v[120:123]
	v_mfma_f32_16x16x32_bf16 v[108:111], v[150:153], v[194:197], v[108:111]
	v_mfma_f32_16x16x32_bf16 v[104:107], v[162:165], v[194:197], v[104:107]
	v_mfma_f32_16x16x32_bf16 v[92:95], v[150:153], v[208:211], v[92:95]
	v_mfma_f32_16x16x32_bf16 v[88:91], v[162:165], v[208:211], v[88:91]
	v_mfma_f32_16x16x32_bf16 v[76:79], v[150:153], v[216:219], v[76:79]
	v_mfma_f32_16x16x32_bf16 v[72:75], v[162:165], v[216:219], v[72:75]
	v_mfma_f32_16x16x32_bf16 v[124:127], v[158:161], v[190:193], v[124:127]
	v_mfma_f32_16x16x32_bf16 v[120:123], v[166:169], v[190:193], v[120:123]
	v_mfma_f32_16x16x32_bf16 v[108:111], v[158:161], v[198:201], v[108:111]
	v_mfma_f32_16x16x32_bf16 v[104:107], v[166:169], v[198:201], v[104:107]
	v_mfma_f32_16x16x32_bf16 v[92:95], v[158:161], v[212:215], v[92:95]
	v_mfma_f32_16x16x32_bf16 v[88:91], v[166:169], v[212:215], v[88:91]
	v_mfma_f32_16x16x32_bf16 v[76:79], v[158:161], v[220:223], v[76:79]
	v_mfma_f32_16x16x32_bf16 v[72:75], v[166:169], v[220:223], v[72:75]
	s_setprio 0
	s_setprio 1
	v_mfma_f32_16x16x32_bf16 v[116:119], v[170:173], v[186:189], v[116:119]
	v_mfma_f32_16x16x32_bf16 v[112:115], v[178:181], v[186:189], v[112:115]
	v_mfma_f32_16x16x32_bf16 v[100:103], v[170:173], v[194:197], v[100:103]
	v_mfma_f32_16x16x32_bf16 v[96:99], v[178:181], v[194:197], v[96:99]
	v_mfma_f32_16x16x32_bf16 v[84:87], v[170:173], v[208:211], v[84:87]
	v_mfma_f32_16x16x32_bf16 v[80:83], v[178:181], v[208:211], v[80:83]
	v_mfma_f32_16x16x32_bf16 v[68:71], v[170:173], v[216:219], v[68:71]
	v_mfma_f32_16x16x32_bf16 v[64:67], v[178:181], v[216:219], v[64:67]
	v_mfma_f32_16x16x32_bf16 v[116:119], v[174:177], v[190:193], v[116:119]
	v_mfma_f32_16x16x32_bf16 v[112:115], v[182:185], v[190:193], v[112:115]
	v_mfma_f32_16x16x32_bf16 v[100:103], v[174:177], v[198:201], v[100:103]
	v_mfma_f32_16x16x32_bf16 v[96:99], v[182:185], v[198:201], v[96:99]
	v_mfma_f32_16x16x32_bf16 v[84:87], v[174:177], v[212:215], v[84:87]
	v_mfma_f32_16x16x32_bf16 v[80:83], v[182:185], v[212:215], v[80:83]
	v_mfma_f32_16x16x32_bf16 v[68:71], v[174:177], v[220:223], v[68:71]
	v_mfma_f32_16x16x32_bf16 v[64:67], v[182:185], v[220:223], v[64:67]
	s_setprio 0
	s_barrier
; #define PG8_STAGE(bufoff, gbase, voff) do { _Pragma("unroll") for (int _i = 0; _i < 2; ++_i) \
;         __builtin_amdgcn_global_load_lds((const unsigned*)((const char*)(gbase) + (voff)[_i]), (PG8_LAS unsigned*)(lds + (bufoff) + ldsw + _i * 8192), 16, 0, 0); } while (0)
; #define PG8_LDA(dst, b, h) do { _Pragma("unroll") for (int m = 0; m < 4; ++m) _Pragma("unroll") for (int k = 0; k < 2; ++k) dst[m][k] = *(const PG8_LAS bf16x8*)(lds + PG8_SA(b, h) + aoff + m * 2048 + k * 1024); } while (0)
; #define PG8_MMA(ai, bj, At, Bt) do { __builtin_amdgcn_s_setprio(1); _Pragma("unroll") for (int m = 0; m < 4; ++m) _Pragma("unroll") for (int n = 0; n < 2; ++n) _Pragma("unroll") for (int k = 0; k < 2; ++k) \
;         acc[ai][bj][m][n] = __builtin_amdgcn_mfma_f32_16x16x32_bf16(Bt[n][k], At[m][k], acc[ai][bj][m][n], 0, 0, 0); __builtin_amdgcn_s_setprio(0); } while (0)
; #define PG8_WAIT_V(n) asm volatile("s_waitcnt vmcnt(" #n ")" ::: "memory")
; #define PG8_WAIT_L(n) asm volatile("s_waitcnt lgkmcnt(" #n ")" ::: "memory")
; #define PG8_BAR __builtin_amdgcn_s_barrier()
; #define PG8_SCHED __builtin_amdgcn_sched_barrier(0)
; template <class Epi, class Sched, bool ALIGN_EPI = false, bool SP2 = false>
; __device__ __forceinline__ void gemm_phase(PG8_LAS unsigned char* lds, const Gemm g, const Sched& S, const Epi& E) {
;     ...
;         for (int t = 0; t < nt; t += 2) {
;             const bool last = (t == nt - 2);
;             const char* a1 = cA + (size_t)(t + 1) * kstep;
;             const char* a2 = last ? nA : cA + (size_t)(t + 2) * kstep; const char* b2 = last ? nB : cB + (size_t)(t + 2) * kstep;
;     ...
;             PG8_LDA(At, 1, 1); PG8_STAGE(PG8_SB(1, 0), b3, voffB); PG8_STAGE(PG8_SB(1, 1), b3 + hstep, voffB); PG8_STAGE(PG8_SA(1, 0), a3, voffA);
;             PG8_WAIT_V(8); PG8_WAIT_L(0); PG8_BAR; PG8_MMA(1, 0, At, B0); PG8_MMA(1, 1, At, B1); PG8_BAR; PG8_SCHED;
	s_add_i32 s42, s76, s48
	v_lshl_add_u64 v[202:203], v[202:203], 0, s[34:35]
	s_mov_b32 m0, s42
	ds_read_b128 v[186:189], v157 offset:49152
	ds_read_b128 v[190:193], v157 offset:50176
	ds_read_b128 v[194:197], v157 offset:51200
	ds_read_b128 v[198:201], v157 offset:52224
	ds_read_b128 v[208:211], v157 offset:53248
	ds_read_b128 v[212:215], v157 offset:54272
	ds_read_b128 v[216:219], v157 offset:55296
	ds_read_b128 v[220:223], v157 offset:56320
	global_load_lds_dwordx4 v[202:203], off
	s_add_i32 m0, s42, 0x2000
	s_add_u32 s26, s26, 0x40080
	v_lshl_add_u64 v[202:203], v[224:225], 0, s[34:35]
	s_addc_u32 s27, s27, 0
	s_add_i32 s42, s77, s48
	global_load_lds_dwordx4 v[202:203], off
	v_lshl_add_u64 v[202:203], s[26:27], 0, v[138:139]
	s_mov_b32 m0, s42
	s_nop 0
	global_load_lds_dwordx4 v[202:203], off
	v_lshl_add_u64 v[202:203], s[26:27], 0, v[128:129]
	s_add_i32 m0, s42, 0x2000
	s_nop 0
	global_load_lds_dwordx4 v[202:203], off
	v_lshl_add_u64 v[202:203], v[226:227], 0, s[34:35]
	s_mov_b32 m0, s55
	s_nop 0
	global_load_lds_dwordx4 v[202:203], off
	v_lshl_add_u64 v[202:203], v[228:229], 0, s[34:35]
	s_mov_b32 m0, s58
	s_nop 0
	global_load_lds_dwordx4 v[202:203], off
	s_waitcnt vmcnt(8)
	s_waitcnt lgkmcnt(0)
	s_barrier
	s_setprio 1
	s_waitcnt lgkmcnt(0)
	v_mfma_f32_16x16x32_bf16 v[60:63], v[150:153], v[186:189], v[60:63]
	v_mfma_f32_16x16x32_bf16 v[56:59], v[162:165], v[186:189], v[56:59]
	v_mfma_f32_16x16x32_bf16 v[44:47], v[150:153], v[194:197], v[44:47]
	v_mfma_f32_16x16x32_bf16 v[40:43], v[162:165], v[194:197], v[40:43]
	v_mfma_f32_16x16x32_bf16 v[28:31], v[150:153], v[208:211], v[28:31]
	v_mfma_f32_16x16x32_bf16 v[24:27], v[162:165], v[208:211], v[24:27]
	v_mfma_f32_16x16x32_bf16 v[12:15], v[150:153], v[216:219], v[12:15]
	v_mfma_f32_16x16x32_bf16 v[8:11], v[162:165], v[216:219], v[8:11]
	v_mfma_f32_16x16x32_bf16 v[60:63], v[158:161], v[190:193], v[60:63]
	v_mfma_f32_16x16x32_bf16 v[56:59], v[166:169], v[190:193], v[56:59]
	v_mfma_f32_16x16x32_bf16 v[44:47], v[158:161], v[198:201], v[44:47]
	v_mfma_f32_16x16x32_bf16 v[40:43], v[166:169], v[198:201], v[40:43]
	v_mfma_f32_16x16x32_bf16 v[28:31], v[158:161], v[212:215], v[28:31]
	v_mfma_f32_16x16x32_bf16 v[24:27], v[166:169], v[212:215], v[24:27]
	v_mfma_f32_16x16x32_bf16 v[12:15], v[158:161], v[220:223], v[12:15]
	v_mfma_f32_16x16x32_bf16 v[8:11], v[166:169], v[220:223], v[8:11]
	s_setprio 0
	s_setprio 1
	v_mfma_f32_16x16x32_bf16 v[52:55], v[170:173], v[186:189], v[52:55]
	s_add_i32 s93, s93, 2
	s_add_u32 s24, s24, 0x100
	s_addc_u32 s25, s25, 0
	v_mfma_f32_16x16x32_bf16 v[48:51], v[178:181], v[186:189], v[48:51]
	s_add_u32 s36, s36, 0x100
	s_addc_u32 s37, s37, 0
	s_add_u32 s26, s24, 0xfffc0080
	v_mfma_f32_16x16x32_bf16 v[36:39], v[170:173], v[194:197], v[36:39]
	s_addc_u32 s27, s25, -1
	s_add_i32 s76, 0, 0x10000
	s_cmp_eq_u32 s93, 12
	v_mfma_f32_16x16x32_bf16 v[32:35], v[178:181], v[194:197], v[32:35]
	s_cselect_b32 s43, s75, s27
	s_cselect_b32 s42, s89, s26
	s_cselect_b32 s27, s61, s37
	v_mfma_f32_16x16x32_bf16 v[20:23], v[170:173], v[208:211], v[20:23]
	s_cselect_b32 s26, s92, s36
	s_add_i32 s77, 0, 0x14000
	s_cmp_gt_u32 s93, 13
	v_mfma_f32_16x16x32_bf16 v[16:19], v[178:181], v[208:211], v[16:19]
	v_mfma_f32_16x16x32_bf16 v[4:7], v[170:173], v[216:219], v[4:7]
	v_mfma_f32_16x16x32_bf16 v[0:3], v[178:181], v[216:219], v[0:3]
	v_mfma_f32_16x16x32_bf16 v[52:55], v[174:177], v[190:193], v[52:55]
	v_mfma_f32_16x16x32_bf16 v[48:51], v[182:185], v[190:193], v[48:51]
	v_mfma_f32_16x16x32_bf16 v[36:39], v[174:177], v[198:201], v[36:39]
	v_mfma_f32_16x16x32_bf16 v[32:35], v[182:185], v[198:201], v[32:35]
	v_mfma_f32_16x16x32_bf16 v[20:23], v[174:177], v[212:215], v[20:23]
	v_mfma_f32_16x16x32_bf16 v[16:19], v[182:185], v[212:215], v[16:19]
	v_mfma_f32_16x16x32_bf16 v[4:7], v[174:177], v[220:223], v[4:7]
	v_mfma_f32_16x16x32_bf16 v[0:3], v[182:185], v[220:223], v[0:3]
	s_setprio 0
	s_barrier
	s_cbranch_scc0 .LBB0_1152
	v_readlane_b32 s76, v250, 21
	v_readlane_b32 s92, v250, 23
	s_and_b64 vcc, exec, s[40:41]
	v_readlane_b32 s77, v250, 22
	v_readlane_b32 s93, v250, 24
	s_cbranch_vccz .LBB0_1155
	s_barrier

; template <class Epi, class Sched, bool ALIGN_EPI = false, bool SP2 = false>
; __device__ __forceinline__ void gemm_phase(PG8_LAS unsigned char* lds, const Gemm g, const Sched& S, const Epi& E) {
;     ...
;         const bool has_next = S.next(ui + 1, nxt);
;         const char* nA = has_next ? (const char*)g.A + (size_t)nxt.pm * tstep : cA; const char* nB = has_next ? (const char*)g.Bt + (size_t)nxt.pn * tstep : cB;
;         for (int t = 0; t < nt; t += 2) {
;             const bool last = (t == nt - 2);
;             const char* a1 = cA + (size_t)(t + 1) * kstep;
;             const char* a2 = last ? nA : cA + (size_t)(t + 2) * kstep; const char* b2 = last ? nB : cB + (size_t)(t + 2) * kstep;
;     ...
; #pragma unroll
;         for (int a = 0; a < 2; ++a)
; #pragma unroll
;             for (int b = 0; b < 2; ++b)
; #pragma unroll
;                 for (int m = 0; m < 4; ++m)
; #pragma unroll
;                     for (int n = 0; n < 2; ++n) acc[a][b][m][n] = (f32x4){0.f, 0.f, 0.f, 0.f};
;         cur = nxt; cA = nA; cB = nB; ++ui;
.LBB0_1228:
	s_ashr_i32 s59, s58, 31
	s_lshl_b64 s[40:41], s[58:59], 21
	s_add_u32 s46, s78, s40
	s_addc_u32 s47, s79, s41
	s_and_b64 s[40:41], s[38:39], exec
	s_cselect_b32 s59, s47, s25
	s_cselect_b32 vcc_lo, s46, s24
	s_ashr_i32 s75, s74, 31
	s_lshl_b64 s[40:41], s[74:75], 21
	s_add_u32 s48, s42, s40
	s_addc_u32 s49, s43, s41
	s_and_b64 s[40:41], s[38:39], exec
	s_cselect_b32 s75, s49, s27
	s_cselect_b32 vcc_hi, s48, s26
	s_add_u32 s24, s24, 0x100080
	s_addc_u32 s25, s25, 0
	s_add_u32 s94, s26, 0x100
	v_mov_b32_e32 v0, 0
	s_addc_u32 s95, s27, 0
	s_mov_b32 s96, -2
	s_waitcnt lgkmcnt(0)
	v_mov_b32_e32 v1, v0
	v_mov_b32_e32 v2, v0
	v_mov_b32_e32 v3, v0
	v_mov_b32_e32 v4, v0
	v_mov_b32_e32 v5, v0
	v_mov_b32_e32 v6, v0
	v_mov_b32_e32 v7, v0
	v_mov_b32_e32 v16, v0
	v_mov_b32_e32 v17, v0
	v_mov_b32_e32 v18, v0
	v_mov_b32_e32 v19, v0
	v_mov_b32_e32 v20, v0
	v_mov_b32_e32 v21, v0
	v_mov_b32_e32 v22, v0
	v_mov_b32_e32 v23, v0
	s_waitcnt vmcnt(0)
	v_mov_b32_e32 v32, v0
	v_mov_b32_e32 v33, v0
	v_mov_b32_e32 v34, v0
	v_mov_b32_e32 v35, v0
	v_mov_b32_e32 v36, v0
	v_mov_b32_e32 v37, v0
	v_mov_b32_e32 v38, v0
	v_mov_b32_e32 v39, v0
	v_mov_b32_e32 v48, v0
	v_mov_b32_e32 v49, v0
	v_mov_b32_e32 v50, v0
	v_mov_b32_e32 v51, v0
	v_mov_b32_e32 v52, v0
	v_mov_b32_e32 v53, v0
	v_mov_b32_e32 v54, v0
	v_mov_b32_e32 v55, v0
	v_mov_b32_e32 v8, v0
	v_mov_b32_e32 v9, v0
	v_mov_b32_e32 v10, v0
	v_mov_b32_e32 v11, v0
	v_mov_b32_e32 v12, v0
	v_mov_b32_e32 v13, v0
	v_mov_b32_e32 v14, v0
	v_mov_b32_e32 v15, v0
	v_mov_b32_e32 v24, v0
	v_mov_b32_e32 v25, v0
	v_mov_b32_e32 v26, v0
	v_mov_b32_e32 v27, v0
	v_mov_b32_e32 v28, v0
	v_mov_b32_e32 v29, v0
	v_mov_b32_e32 v30, v0
	v_mov_b32_e32 v31, v0
	v_mov_b32_e32 v40, v0
	v_mov_b32_e32 v41, v0
	v_mov_b32_e32 v42, v0
	v_mov_b32_e32 v43, v0
	v_mov_b32_e32 v44, v0
	v_mov_b32_e32 v45, v0
	v_mov_b32_e32 v46, v0
	v_mov_b32_e32 v47, v0
	v_mov_b32_e32 v56, v0
	v_mov_b32_e32 v57, v0
	v_mov_b32_e32 v58, v0
	v_mov_b32_e32 v59, v0
	v_mov_b32_e32 v60, v0
	v_mov_b32_e32 v61, v0
	v_mov_b32_e32 v62, v0
	v_mov_b32_e32 v63, v0
	v_mov_b32_e32 v64, v0
	v_mov_b32_e32 v65, v0
	v_mov_b32_e32 v66, v0
	v_mov_b32_e32 v67, v0
	v_mov_b32_e32 v68, v0
	v_mov_b32_e32 v69, v0
	v_mov_b32_e32 v70, v0
	v_mov_b32_e32 v71, v0
	v_mov_b32_e32 v80, v0
	v_mov_b32_e32 v81, v0
	v_mov_b32_e32 v82, v0
	v_mov_b32_e32 v83, v0
	v_mov_b32_e32 v84, v0
	v_mov_b32_e32 v85, v0
	v_mov_b32_e32 v86, v0
	v_mov_b32_e32 v87, v0
	v_mov_b32_e32 v96, v0
	v_mov_b32_e32 v97, v0
	v_mov_b32_e32 v98, v0
	v_mov_b32_e32 v99, v0
	v_mov_b32_e32 v100, v0
	v_mov_b32_e32 v101, v0
	v_mov_b32_e32 v102, v0
	v_mov_b32_e32 v103, v0
	v_mov_b32_e32 v112, v0
	v_mov_b32_e32 v113, v0
	v_mov_b32_e32 v114, v0
	v_mov_b32_e32 v115, v0
	v_mov_b32_e32 v116, v0
	v_mov_b32_e32 v117, v0
	v_mov_b32_e32 v118, v0
	v_mov_b32_e32 v119, v0
	v_mov_b32_e32 v72, v0
	v_mov_b32_e32 v73, v0
	v_mov_b32_e32 v74, v0
	v_mov_b32_e32 v75, v0
	v_mov_b32_e32 v76, v0
	v_mov_b32_e32 v77, v0
	v_mov_b32_e32 v78, v0
	v_mov_b32_e32 v79, v0
	v_mov_b32_e32 v88, v0
	v_mov_b32_e32 v89, v0
	v_mov_b32_e32 v90, v0
	v_mov_b32_e32 v91, v0
	v_mov_b32_e32 v92, v0
	v_mov_b32_e32 v93, v0
	v_mov_b32_e32 v94, v0
	v_mov_b32_e32 v95, v0
	v_mov_b32_e32 v104, v0
	v_mov_b32_e32 v105, v0
	v_mov_b32_e32 v106, v0
	v_mov_b32_e32 v107, v0
	v_mov_b32_e32 v108, v0
	v_mov_b32_e32 v109, v0
	v_mov_b32_e32 v110, v0
	v_mov_b32_e32 v111, v0
	v_mov_b32_e32 v120, v0
	v_mov_b32_e32 v121, v0
	v_mov_b32_e32 v122, v0
	v_mov_b32_e32 v123, v0
	v_mov_b32_e32 v124, v0
	v_mov_b32_e32 v125, v0
	v_mov_b32_e32 v126, v0
	v_mov_b32_e32 v127, v0
	s_add_u32 s26, s24, 0xfff00080
	s_addc_u32 s27, s25, -1
	s_add_i32 s76, 0, 0x10000
	s_cmp_eq_u32 s96, 60
	s_cselect_b32 s41, s59, s27
	s_cselect_b32 s40, vcc_lo, s26
	s_cselect_b32 s27, s75, s95
	s_cselect_b32 s26, vcc_hi, s94
	s_add_i32 s97, 0, 0x14000
.LBB0_1229:
	v_add_u32_e32 v138, s76, v157
	ds_read_b128 v[152:155], v138
	ds_read_b128 v[160:163], v138 offset:1024
	ds_read_b128 v[164:167], v138 offset:2048
	ds_read_b128 v[168:171], v138 offset:3072
	v_add_u32_e32 v138, s97, v157
	ds_read_b128 v[172:175], v138
	ds_read_b128 v[176:179], v138 offset:1024
	ds_read_b128 v[180:183], v138 offset:2048
	ds_read_b128 v[184:187], v138 offset:3072
	v_lshl_add_u64 v[224:225], s[24:25], 0, v[148:149]
	s_add_i32 m0, s55, 0xc000
	ds_read_b128 v[188:191], v159
	ds_read_b128 v[192:195], v159 offset:1024
	ds_read_b128 v[196:199], v159 offset:2048
	ds_read_b128 v[200:203], v159 offset:3072
	ds_read_b128 v[208:211], v159 offset:4096
	ds_read_b128 v[212:215], v159 offset:5120
	ds_read_b128 v[216:219], v159 offset:6144
	ds_read_b128 v[220:223], v159 offset:7168
	global_load_lds_dwordx4 v[224:225], off
	v_lshl_add_u64 v[224:225], s[24:25], 0, v[150:151]
	s_add_i32 m0, s55, 0xe000
	s_nop 0
	global_load_lds_dwordx4 v[224:225], off
	s_waitcnt vmcnt(8)
	s_waitcnt lgkmcnt(0)
	s_barrier
; #define PG8_STAGE(bufoff, gbase, voff) do { _Pragma("unroll") for (int _i = 0; _i < 2; ++_i) \
;         __builtin_amdgcn_global_load_lds((const unsigned*)((const char*)(gbase) + (voff)[_i]), (PG8_LAS unsigned*)(lds + (bufoff) + ldsw + _i * 8192), 16, 0, 0); } while (0)
; #define PG8_LDA(dst, b, h) do { _Pragma("unroll") for (int m = 0; m < 4; ++m) _Pragma("unroll") for (int k = 0; k < 2; ++k) dst[m][k] = *(const PG8_LAS bf16x8*)(lds + PG8_SA(b, h) + aoff + m * 2048 + k * 1024); } while (0)
; #define PG8_LDB(dst, b, h) do { _Pragma("unroll") for (int n = 0; n < 2; ++n) _Pragma("unroll") for (int k = 0; k < 2; ++k) dst[n][k] = *(const PG8_LAS bf16x8*)(lds + PG8_SB(b, h) + boff + n * 2048 + k * 1024); } while (0)
; #define PG8_MMA(ai, bj, At, Bt) do { __builtin_amdgcn_s_setprio(1); _Pragma("unroll") for (int m = 0; m < 4; ++m) _Pragma("unroll") for (int n = 0; n < 2; ++n) _Pragma("unroll") for (int k = 0; k < 2; ++k) \
;         acc[ai][bj][m][n] = __builtin_amdgcn_mfma_f32_16x16x32_bf16(Bt[n][k], At[m][k], acc[ai][bj][m][n], 0, 0, 0); __builtin_amdgcn_s_setprio(0); } while (0)
; #define PG8_WAIT_V(n) asm volatile("s_waitcnt vmcnt(" #n ")" ::: "memory")
; #define PG8_WAIT_L(n) asm volatile("s_waitcnt lgkmcnt(" #n ")" ::: "memory")
; #define PG8_BAR __builtin_amdgcn_s_barrier()
; #define PG8_SCHED __builtin_amdgcn_sched_barrier(0)
; template <class Epi, class Sched, bool ALIGN_EPI = false, bool SP2 = false>
; __device__ __forceinline__ void gemm_phase(PG8_LAS unsigned char* lds, const Gemm g, const Sched& S, const Epi& E) {
;     ...
;             PG8_LDB(B0, 0, 0); PG8_LDB(B1, 0, 1); PG8_SCHED; PG8_LDA(At, 0, 0); PG8_STAGE(PG8_SA(1, 1), a1 + hstep, voffA);
;             PG8_WAIT_V(8); PG8_WAIT_L(0); PG8_BAR; PG8_MMA(0, 0, At, B0); PG8_MMA(0, 1, At, B1); PG8_BAR; PG8_SCHED;
;             PG8_LDA(At, 0, 1); PG8_STAGE(PG8_SB(0, 0), b2, voffB); PG8_STAGE(PG8_SB(0, 1), b2 + hstep, voffB); PG8_STAGE(PG8_SA(0, 0), a2, voffA);
;             PG8_WAIT_V(8); PG8_WAIT_L(0); PG8_BAR; PG8_MMA(1, 0, At, B0); PG8_MMA(1, 1, At, B1); PG8_BAR; PG8_SCHED;
	s_setprio 1
	s_waitcnt lgkmcnt(0)
	v_mfma_f32_16x16x32_bf16 v[124:127], v[152:155], v[188:191], v[124:127]
	v_mfma_f32_16x16x32_bf16 v[120:123], v[164:167], v[188:191], v[120:123]
	v_mfma_f32_16x16x32_bf16 v[108:111], v[152:155], v[196:199], v[108:111]
	v_mfma_f32_16x16x32_bf16 v[104:107], v[164:167], v[196:199], v[104:107]
	v_mfma_f32_16x16x32_bf16 v[92:95], v[152:155], v[208:211], v[92:95]
	v_mfma_f32_16x16x32_bf16 v[88:91], v[164:167], v[208:211], v[88:91]
	v_mfma_f32_16x16x32_bf16 v[76:79], v[152:155], v[216:219], v[76:79]
	v_mfma_f32_16x16x32_bf16 v[72:75], v[164:167], v[216:219], v[72:75]
	v_mfma_f32_16x16x32_bf16 v[124:127], v[160:163], v[192:195], v[124:127]
	v_mfma_f32_16x16x32_bf16 v[120:123], v[168:171], v[192:195], v[120:123]
	v_mfma_f32_16x16x32_bf16 v[108:111], v[160:163], v[200:203], v[108:111]
	v_mfma_f32_16x16x32_bf16 v[104:107], v[168:171], v[200:203], v[104:107]
	v_mfma_f32_16x16x32_bf16 v[92:95], v[160:163], v[212:215], v[92:95]
	v_mfma_f32_16x16x32_bf16 v[88:91], v[168:171], v[212:215], v[88:91]
	v_mfma_f32_16x16x32_bf16 v[76:79], v[160:163], v[220:223], v[76:79]
	v_mfma_f32_16x16x32_bf16 v[72:75], v[168:171], v[220:223], v[72:75]
	s_setprio 0
	s_setprio 1
	v_mfma_f32_16x16x32_bf16 v[116:119], v[172:175], v[188:191], v[116:119]
	v_mfma_f32_16x16x32_bf16 v[112:115], v[180:183], v[188:191], v[112:115]
	v_mfma_f32_16x16x32_bf16 v[100:103], v[172:175], v[196:199], v[100:103]
	v_mfma_f32_16x16x32_bf16 v[96:99], v[180:183], v[196:199], v[96:99]
	v_mfma_f32_16x16x32_bf16 v[84:87], v[172:175], v[208:211], v[84:87]
	v_mfma_f32_16x16x32_bf16 v[80:83], v[180:183], v[208:211], v[80:83]
	v_mfma_f32_16x16x32_bf16 v[68:71], v[172:175], v[216:219], v[68:71]
	v_mfma_f32_16x16x32_bf16 v[64:67], v[180:183], v[216:219], v[64:67]
	v_mfma_f32_16x16x32_bf16 v[116:119], v[176:179], v[192:195], v[116:119]
	v_mfma_f32_16x16x32_bf16 v[112:115], v[184:187], v[192:195], v[112:115]
	v_mfma_f32_16x16x32_bf16 v[100:103], v[176:179], v[200:203], v[100:103]
	v_mfma_f32_16x16x32_bf16 v[96:99], v[184:187], v[200:203], v[96:99]
	v_mfma_f32_16x16x32_bf16 v[84:87], v[176:179], v[212:215], v[84:87]
	v_mfma_f32_16x16x32_bf16 v[80:83], v[184:187], v[212:215], v[80:83]
	v_mfma_f32_16x16x32_bf16 v[68:71], v[176:179], v[220:223], v[68:71]
	v_mfma_f32_16x16x32_bf16 v[64:67], v[184:187], v[220:223], v[64:67]
	s_setprio 0
	s_barrier
	s_add_i32 s76, s76, s54
	v_lshl_add_u64 v[224:225], s[26:27], 0, v[132:133]
	s_mov_b32 m0, s76
	ds_read_b128 v[188:191], v159 offset:16384
	ds_read_b128 v[192:195], v159 offset:17408
	ds_read_b128 v[196:199], v159 offset:18432
	ds_read_b128 v[200:203], v159 offset:19456
	ds_read_b128 v[208:211], v159 offset:20480
	ds_read_b128 v[212:215], v159 offset:21504
	ds_read_b128 v[216:219], v159 offset:22528
	ds_read_b128 v[220:223], v159 offset:23552
	global_load_lds_dwordx4 v[224:225], off
	s_add_i32 m0, s76, 0x2000
	s_add_u32 s76, s26, 0x100000
	v_lshl_add_u64 v[226:227], s[26:27], 0, v[128:129]
	s_addc_u32 s77, s27, 0
	s_add_i32 s97, s97, s54
	global_load_lds_dwordx4 v[226:227], off
	v_lshl_add_u64 v[228:229], s[76:77], 0, v[132:133]
	s_mov_b32 m0, s97
	v_lshl_add_u64 v[230:231], s[40:41], 0, v[130:131]
	global_load_lds_dwordx4 v[228:229], off
	v_lshl_add_u64 v[228:229], s[76:77], 0, v[128:129]
	s_add_i32 m0, s97, 0x2000
	s_nop 0
	global_load_lds_dwordx4 v[228:229], off
	v_lshl_add_u64 v[228:229], s[40:41], 0, v[134:135]
	s_mov_b32 m0, s55
	s_nop 0
	global_load_lds_dwordx4 v[228:229], off
	s_mov_b32 m0, s88
	s_nop 0
	global_load_lds_dwordx4 v[230:231], off
	s_waitcnt vmcnt(8)
	s_waitcnt lgkmcnt(0)
	s_barrier
	s_setprio 1
	s_waitcnt lgkmcnt(0)
	v_mfma_f32_16x16x32_bf16 v[60:63], v[152:155], v[188:191], v[60:63]
	v_mfma_f32_16x16x32_bf16 v[56:59], v[164:167], v[188:191], v[56:59]
	v_mfma_f32_16x16x32_bf16 v[44:47], v[152:155], v[196:199], v[44:47]
	v_mfma_f32_16x16x32_bf16 v[40:43], v[164:167], v[196:199], v[40:43]
	v_mfma_f32_16x16x32_bf16 v[28:31], v[152:155], v[208:211], v[28:31]
	v_mfma_f32_16x16x32_bf16 v[24:27], v[164:167], v[208:211], v[24:27]
	v_mfma_f32_16x16x32_bf16 v[12:15], v[152:155], v[216:219], v[12:15]
	v_mfma_f32_16x16x32_bf16 v[8:11], v[164:167], v[216:219], v[8:11]
	v_mfma_f32_16x16x32_bf16 v[60:63], v[160:163], v[192:195], v[60:63]
	v_mfma_f32_16x16x32_bf16 v[56:59], v[168:171], v[192:195], v[56:59]
	v_mfma_f32_16x16x32_bf16 v[44:47], v[160:163], v[200:203], v[44:47]
	v_mfma_f32_16x16x32_bf16 v[40:43], v[168:171], v[200:203], v[40:43]
	v_mfma_f32_16x16x32_bf16 v[28:31], v[160:163], v[212:215], v[28:31]
	v_mfma_f32_16x16x32_bf16 v[24:27], v[168:171], v[212:215], v[24:27]
	v_mfma_f32_16x16x32_bf16 v[12:15], v[160:163], v[220:223], v[12:15]
	v_mfma_f32_16x16x32_bf16 v[8:11], v[168:171], v[220:223], v[8:11]
	s_setprio 0
	s_setprio 1
	v_mfma_f32_16x16x32_bf16 v[52:55], v[172:175], v[188:191], v[52:55]
	v_mfma_f32_16x16x32_bf16 v[48:51], v[180:183], v[188:191], v[48:51]
	v_mfma_f32_16x16x32_bf16 v[36:39], v[172:175], v[196:199], v[36:39]
	v_mfma_f32_16x16x32_bf16 v[32:35], v[180:183], v[196:199], v[32:35]
	v_mfma_f32_16x16x32_bf16 v[20:23], v[172:175], v[208:211], v[20:23]
	v_mfma_f32_16x16x32_bf16 v[16:19], v[180:183], v[208:211], v[16:19]
	v_mfma_f32_16x16x32_bf16 v[4:7], v[172:175], v[216:219], v[4:7]
	v_mfma_f32_16x16x32_bf16 v[0:3], v[180:183], v[216:219], v[0:3]
	v_mfma_f32_16x16x32_bf16 v[52:55], v[176:179], v[192:195], v[52:55]
	v_mfma_f32_16x16x32_bf16 v[48:51], v[184:187], v[192:195], v[48:51]
	v_mfma_f32_16x16x32_bf16 v[36:39], v[176:179], v[200:203], v[36:39]
	v_mfma_f32_16x16x32_bf16 v[32:35], v[184:187], v[200:203], v[32:35]
	v_mfma_f32_16x16x32_bf16 v[20:23], v[176:179], v[212:215], v[20:23]
	v_mfma_f32_16x16x32_bf16 v[16:19], v[184:187], v[212:215], v[16:19]
	v_mfma_f32_16x16x32_bf16 v[4:7], v[176:179], v[220:223], v[4:7]
	v_mfma_f32_16x16x32_bf16 v[0:3], v[184:187], v[220:223], v[0:3]
	s_setprio 0
	s_barrier
; #define PG8_STAGE(bufoff, gbase, voff) do { _Pragma("unroll") for (int _i = 0; _i < 2; ++_i) \
;         __builtin_amdgcn_global_load_lds((const unsigned*)((const char*)(gbase) + (voff)[_i]), (PG8_LAS unsigned*)(lds + (bufoff) + ldsw + _i * 8192), 16, 0, 0); } while (0)
; #define PG8_LDA(dst, b, h) do { _Pragma("unroll") for (int m = 0; m < 4; ++m) _Pragma("unroll") for (int k = 0; k < 2; ++k) dst[m][k] = *(const PG8_LAS bf16x8*)(lds + PG8_SA(b, h) + aoff + m * 2048 + k * 1024); } while (0)
; #define PG8_LDB(dst, b, h) do { _Pragma("unroll") for (int n = 0; n < 2; ++n) _Pragma("unroll") for (int k = 0; k < 2; ++k) dst[n][k] = *(const PG8_LAS bf16x8*)(lds + PG8_SB(b, h) + boff + n * 2048 + k * 1024); } while (0)
; #define PG8_MMA(ai, bj, At, Bt) do { __builtin_amdgcn_s_setprio(1); _Pragma("unroll") for (int m = 0; m < 4; ++m) _Pragma("unroll") for (int n = 0; n < 2; ++n) _Pragma("unroll") for (int k = 0; k < 2; ++k) \
;         acc[ai][bj][m][n] = __builtin_amdgcn_mfma_f32_16x16x32_bf16(Bt[n][k], At[m][k], acc[ai][bj][m][n], 0, 0, 0); __builtin_amdgcn_s_setprio(0); } while (0)
; #define PG8_WAIT_V(n) asm volatile("s_waitcnt vmcnt(" #n ")" ::: "memory")
; #define PG8_WAIT_L(n) asm volatile("s_waitcnt lgkmcnt(" #n ")" ::: "memory")
; #define PG8_BAR __builtin_amdgcn_s_barrier()
; #define PG8_SCHED __builtin_amdgcn_sched_barrier(0)
; template <class Epi, class Sched, bool ALIGN_EPI = false, bool SP2 = false>
; __device__ __forceinline__ void gemm_phase(PG8_LAS unsigned char* lds, const Gemm g, const Sched& S, const Epi& E) {
;     ...
;             PG8_LDB(B0, 1, 0); PG8_LDB(B1, 1, 1); PG8_SCHED; PG8_LDA(At, 1, 0); PG8_STAGE(PG8_SA(0, 1), a2 + hstep, voffA);
;             PG8_WAIT_V(8); PG8_WAIT_L(0); PG8_BAR; PG8_MMA(0, 0, At, B0); PG8_MMA(0, 1, At, B1); PG8_BAR; PG8_SCHED;
	s_add_i32 s76, 0, 0x18000
	v_add_u32_e32 v138, s76, v157
	s_add_i32 s77, 0, 0x1c000
	ds_read_b128 v[152:155], v138
	ds_read_b128 v[160:163], v138 offset:1024
	ds_read_b128 v[164:167], v138 offset:2048
	ds_read_b128 v[168:171], v138 offset:3072
	v_add_u32_e32 v138, s77, v157
	ds_read_b128 v[172:175], v138
	ds_read_b128 v[176:179], v138 offset:1024
	ds_read_b128 v[180:183], v138 offset:2048
	ds_read_b128 v[184:187], v138 offset:3072
	s_add_u32 s40, s40, 0x100000
	s_addc_u32 s41, s41, 0
	s_mov_b32 m0, s89
	v_lshl_add_u64 v[232:233], s[40:41], 0, v[134:135]
	ds_read_b128 v[188:191], v159 offset:32768
	ds_read_b128 v[192:195], v159 offset:33792
	ds_read_b128 v[196:199], v159 offset:34816
	ds_read_b128 v[200:203], v159 offset:35840
	ds_read_b128 v[208:211], v159 offset:36864
	ds_read_b128 v[212:215], v159 offset:37888
	ds_read_b128 v[216:219], v159 offset:38912
	ds_read_b128 v[220:223], v159 offset:39936
	global_load_lds_dwordx4 v[232:233], off
	v_lshl_add_u64 v[232:233], s[40:41], 0, v[130:131]
	s_mov_b32 m0, s30
	s_nop 0
	global_load_lds_dwordx4 v[232:233], off
	s_waitcnt vmcnt(8)
	s_waitcnt lgkmcnt(0)
	s_barrier
	s_setprio 1
	s_waitcnt lgkmcnt(0)
	v_mfma_f32_16x16x32_bf16 v[124:127], v[152:155], v[188:191], v[124:127]
	v_mfma_f32_16x16x32_bf16 v[120:123], v[164:167], v[188:191], v[120:123]
	v_mfma_f32_16x16x32_bf16 v[108:111], v[152:155], v[196:199], v[108:111]
	v_mfma_f32_16x16x32_bf16 v[104:107], v[164:167], v[196:199], v[104:107]
	v_mfma_f32_16x16x32_bf16 v[92:95], v[152:155], v[208:211], v[92:95]
	v_mfma_f32_16x16x32_bf16 v[88:91], v[164:167], v[208:211], v[88:91]
	v_mfma_f32_16x16x32_bf16 v[76:79], v[152:155], v[216:219], v[76:79]
	v_mfma_f32_16x16x32_bf16 v[72:75], v[164:167], v[216:219], v[72:75]
	v_mfma_f32_16x16x32_bf16 v[124:127], v[160:163], v[192:195], v[124:127]
	v_mfma_f32_16x16x32_bf16 v[120:123], v[168:171], v[192:195], v[120:123]
	v_mfma_f32_16x16x32_bf16 v[108:111], v[160:163], v[200:203], v[108:111]
	v_mfma_f32_16x16x32_bf16 v[104:107], v[168:171], v[200:203], v[104:107]
	v_mfma_f32_16x16x32_bf16 v[92:95], v[160:163], v[212:215], v[92:95]
	v_mfma_f32_16x16x32_bf16 v[88:91], v[168:171], v[212:215], v[88:91]
	v_mfma_f32_16x16x32_bf16 v[76:79], v[160:163], v[220:223], v[76:79]
	v_mfma_f32_16x16x32_bf16 v[72:75], v[168:171], v[220:223], v[72:75]
	s_setprio 0
	s_setprio 1
	v_mfma_f32_16x16x32_bf16 v[116:119], v[172:175], v[188:191], v[116:119]
	v_mfma_f32_16x16x32_bf16 v[112:115], v[180:183], v[188:191], v[112:115]
	v_mfma_f32_16x16x32_bf16 v[100:103], v[172:175], v[196:199], v[100:103]
	v_mfma_f32_16x16x32_bf16 v[96:99], v[180:183], v[196:199], v[96:99]
	v_mfma_f32_16x16x32_bf16 v[84:87], v[172:175], v[208:211], v[84:87]
	v_mfma_f32_16x16x32_bf16 v[80:83], v[180:183], v[208:211], v[80:83]
	v_mfma_f32_16x16x32_bf16 v[68:71], v[172:175], v[216:219], v[68:71]
	v_mfma_f32_16x16x32_bf16 v[64:67], v[180:183], v[216:219], v[64:67]
	v_mfma_f32_16x16x32_bf16 v[116:119], v[176:179], v[192:195], v[116:119]
	v_mfma_f32_16x16x32_bf16 v[112:115], v[184:187], v[192:195], v[112:115]
	v_mfma_f32_16x16x32_bf16 v[100:103], v[176:179], v[200:203], v[100:103]
	v_mfma_f32_16x16x32_bf16 v[96:99], v[184:187], v[200:203], v[96:99]
	v_mfma_f32_16x16x32_bf16 v[84:87], v[176:179], v[212:215], v[84:87]
	v_mfma_f32_16x16x32_bf16 v[80:83], v[184:187], v[212:215], v[80:83]
	v_mfma_f32_16x16x32_bf16 v[68:71], v[176:179], v[220:223], v[68:71]
	v_mfma_f32_16x16x32_bf16 v[64:67], v[184:187], v[220:223], v[64:67]
	s_setprio 0
	s_barrier
; #define PG8_STAGE(bufoff, gbase, voff) do { _Pragma("unroll") for (int _i = 0; _i < 2; ++_i) \
;         __builtin_amdgcn_global_load_lds((const unsigned*)((const char*)(gbase) + (voff)[_i]), (PG8_LAS unsigned*)(lds + (bufoff) + ldsw + _i * 8192), 16, 0, 0); } while (0)
; #define PG8_LDA(dst, b, h) do { _Pragma("unroll") for (int m = 0; m < 4; ++m) _Pragma("unroll") for (int k = 0; k < 2; ++k) dst[m][k] = *(const PG8_LAS bf16x8*)(lds + PG8_SA(b, h) + aoff + m * 2048 + k * 1024); } while (0)
; #define PG8_MMA(ai, bj, At, Bt) do { __builtin_amdgcn_s_setprio(1); _Pragma("unroll") for (int m = 0; m < 4; ++m) _Pragma("unroll") for (int n = 0; n < 2; ++n) _Pragma("unroll") for (int k = 0; k < 2; ++k) \
;         acc[ai][bj][m][n] = __builtin_amdgcn_mfma_f32_16x16x32_bf16(Bt[n][k], At[m][k], acc[ai][bj][m][n], 0, 0, 0); __builtin_amdgcn_s_setprio(0); } while (0)
; #define PG8_WAIT_V(n) asm volatile("s_waitcnt vmcnt(" #n ")" ::: "memory")
; #define PG8_WAIT_L(n) asm volatile("s_waitcnt lgkmcnt(" #n ")" ::: "memory")
; #define PG8_BAR __builtin_amdgcn_s_barrier()
; #define PG8_SCHED __builtin_amdgcn_sched_barrier(0)
; template <class Epi, class Sched, bool ALIGN_EPI = false, bool SP2 = false>
; __device__ __forceinline__ void gemm_phase(PG8_LAS unsigned char* lds, const Gemm g, const Sched& S, const Epi& E) {
;     ...
;         for (int t = 0; t < nt; t += 2) {
;             const bool last = (t == nt - 2);
;             const char* a1 = cA + (size_t)(t + 1) * kstep;
;             const char* a2 = last ? nA : cA + (size_t)(t + 2) * kstep; const char* b2 = last ? nB : cB + (size_t)(t + 2) * kstep;
;     ...
;             PG8_LDA(At, 1, 1); PG8_STAGE(PG8_SB(1, 0), b3, voffB); PG8_STAGE(PG8_SB(1, 1), b3 + hstep, voffB); PG8_STAGE(PG8_SA(1, 0), a3, voffA);
;             PG8_WAIT_V(8); PG8_WAIT_L(0); PG8_BAR; PG8_MMA(1, 0, At, B0); PG8_MMA(1, 1, At, B1); PG8_BAR; PG8_SCHED;
	s_add_i32 s40, s76, s54
	v_lshl_add_u64 v[224:225], v[224:225], 0, s[34:35]
	s_mov_b32 m0, s40
	ds_read_b128 v[188:191], v159 offset:49152
	ds_read_b128 v[192:195], v159 offset:50176
	ds_read_b128 v[196:199], v159 offset:51200
	ds_read_b128 v[200:203], v159 offset:52224
	ds_read_b128 v[208:211], v159 offset:53248
	ds_read_b128 v[212:215], v159 offset:54272
	ds_read_b128 v[216:219], v159 offset:55296
	ds_read_b128 v[220:223], v159 offset:56320
	global_load_lds_dwordx4 v[224:225], off
	s_add_i32 m0, s40, 0x2000
	s_add_u32 s26, s26, 0x100080
	v_lshl_add_u64 v[224:225], v[226:227], 0, s[34:35]
	s_addc_u32 s27, s27, 0
	s_add_i32 s40, s77, s54
	global_load_lds_dwordx4 v[224:225], off
	v_lshl_add_u64 v[224:225], s[26:27], 0, v[132:133]
	s_mov_b32 m0, s40
	s_nop 0
	global_load_lds_dwordx4 v[224:225], off
	v_lshl_add_u64 v[224:225], s[26:27], 0, v[128:129]
	s_add_i32 m0, s40, 0x2000
	s_nop 0
	global_load_lds_dwordx4 v[224:225], off
	v_lshl_add_u64 v[224:225], v[228:229], 0, s[34:35]
	s_mov_b32 m0, s1
	s_nop 0
	global_load_lds_dwordx4 v[224:225], off
	v_lshl_add_u64 v[224:225], v[230:231], 0, s[34:35]
	s_mov_b32 m0, s92
	s_nop 0
	global_load_lds_dwordx4 v[224:225], off
	s_waitcnt vmcnt(8)
	s_waitcnt lgkmcnt(0)
	s_barrier
	s_setprio 1
	s_waitcnt lgkmcnt(0)
	v_mfma_f32_16x16x32_bf16 v[60:63], v[152:155], v[188:191], v[60:63]
	v_mfma_f32_16x16x32_bf16 v[56:59], v[164:167], v[188:191], v[56:59]
	v_mfma_f32_16x16x32_bf16 v[44:47], v[152:155], v[196:199], v[44:47]
	v_mfma_f32_16x16x32_bf16 v[40:43], v[164:167], v[196:199], v[40:43]
	v_mfma_f32_16x16x32_bf16 v[28:31], v[152:155], v[208:211], v[28:31]
	v_mfma_f32_16x16x32_bf16 v[24:27], v[164:167], v[208:211], v[24:27]
	v_mfma_f32_16x16x32_bf16 v[12:15], v[152:155], v[216:219], v[12:15]
	v_mfma_f32_16x16x32_bf16 v[8:11], v[164:167], v[216:219], v[8:11]
	v_mfma_f32_16x16x32_bf16 v[60:63], v[160:163], v[192:195], v[60:63]
	v_mfma_f32_16x16x32_bf16 v[56:59], v[168:171], v[192:195], v[56:59]
	v_mfma_f32_16x16x32_bf16 v[44:47], v[160:163], v[200:203], v[44:47]
	v_mfma_f32_16x16x32_bf16 v[40:43], v[168:171], v[200:203], v[40:43]
	v_mfma_f32_16x16x32_bf16 v[28:31], v[160:163], v[212:215], v[28:31]
	v_mfma_f32_16x16x32_bf16 v[24:27], v[168:171], v[212:215], v[24:27]
	v_mfma_f32_16x16x32_bf16 v[12:15], v[160:163], v[220:223], v[12:15]
	v_mfma_f32_16x16x32_bf16 v[8:11], v[168:171], v[220:223], v[8:11]
	s_setprio 0
	s_setprio 1
	v_mfma_f32_16x16x32_bf16 v[52:55], v[172:175], v[188:191], v[52:55]
	s_add_i32 s96, s96, 2
	s_add_u32 s24, s24, 0x100
	s_addc_u32 s25, s25, 0
	v_mfma_f32_16x16x32_bf16 v[48:51], v[180:183], v[188:191], v[48:51]
	s_add_u32 s94, s94, 0x100
	s_addc_u32 s95, s95, 0
	s_add_u32 s26, s24, 0xfff00080
	v_mfma_f32_16x16x32_bf16 v[36:39], v[172:175], v[196:199], v[36:39]
	s_addc_u32 s27, s25, -1
	s_add_i32 s76, 0, 0x10000
	s_cmp_eq_u32 s96, 60
	v_mfma_f32_16x16x32_bf16 v[32:35], v[180:183], v[196:199], v[32:35]
	s_cselect_b32 s41, s59, s27
	s_cselect_b32 s40, vcc_lo, s26
	s_cselect_b32 s27, s75, s95
	v_mfma_f32_16x16x32_bf16 v[20:23], v[172:175], v[208:211], v[20:23]
	s_cselect_b32 s26, vcc_hi, s94
	s_add_i32 s97, 0, 0x14000
	s_cmp_gt_u32 s96, 61
	v_mfma_f32_16x16x32_bf16 v[16:19], v[180:183], v[208:211], v[16:19]
	v_mfma_f32_16x16x32_bf16 v[4:7], v[172:175], v[216:219], v[4:7]
	v_mfma_f32_16x16x32_bf16 v[0:3], v[180:183], v[216:219], v[0:3]
	v_mfma_f32_16x16x32_bf16 v[52:55], v[176:179], v[192:195], v[52:55]
	v_mfma_f32_16x16x32_bf16 v[48:51], v[184:187], v[192:195], v[48:51]
	v_mfma_f32_16x16x32_bf16 v[36:39], v[176:179], v[200:203], v[36:39]
	v_mfma_f32_16x16x32_bf16 v[32:35], v[184:187], v[200:203], v[32:35]
	v_mfma_f32_16x16x32_bf16 v[20:23], v[176:179], v[212:215], v[20:23]
	v_mfma_f32_16x16x32_bf16 v[16:19], v[184:187], v[212:215], v[16:19]
	v_mfma_f32_16x16x32_bf16 v[4:7], v[176:179], v[220:223], v[4:7]
	v_mfma_f32_16x16x32_bf16 v[0:3], v[184:187], v[220:223], v[0:3]
	s_setprio 0
	s_barrier
	s_cbranch_scc0 .LBB0_1229
	s_and_b64 vcc, exec, s[28:29]
	s_cbranch_vccz .LBB0_1232
	s_barrier
